# P.V fragment hoisting also in the B-layer memory-attention items (single spare register set)
# speedup vs baseline: 1.0002x; 1.0001x over previous
.LBB0_89:
	s_or_b64 exec, exec, s[4:5]
	v_and_b32_e32 v5, 64, v229
	v_mov_b32_e32 v1, v4
	v_xor_b32_e32 v4, 16, v229
	v_add_u32_e32 v5, 64, v5
	v_cmp_lt_i32_e32 vcc, v4, v5
	v_and_b32_e32 v71, 15, v52
	v_mad_u32_u24 v79, v71, s14, v72
	v_cndmask_b32_e32 v78, v229, v4, vcc
	v_xor_b32_e32 v4, 32, v229
	v_cmp_lt_i32_e32 vcc, v4, v5
	v_mov_b32_e32 v65, v6
	ds_read_b128 v[8:11], v79 offset:64
	v_cndmask_b32_e32 v73, v229, v4, vcc
	ds_read_b128 v[4:7], v79
	s_waitcnt lgkmcnt(0)
	v_mfma_f32_16x16x32_bf16 v[4:7], v[4:7], v[0:3], 0
	v_lshlrev_b32_e32 v73, 2, v73
	ds_read_b128 v[74:77], v79 offset:32320
	v_mfma_f32_16x16x32_bf16 v[60:63], v[8:11], v[64:67], v[4:7]
	ds_read_b128 v[8:11], v79 offset:2368
	s_nop 3
	ds_read_b128 v[4:7], v79 offset:2304
	s_waitcnt lgkmcnt(0)
	v_mfma_f32_16x16x32_bf16 v[4:7], v[4:7], v[0:3], 0
	v_mfma_f32_16x16x32_bf16 v[56:59], v[8:11], v[64:67], v[4:7]
	ds_read_b128 v[8:11], v79 offset:4672
	s_nop 5
	ds_read_b128 v[4:7], v79 offset:4608
	s_waitcnt lgkmcnt(0)
	v_mfma_f32_16x16x32_bf16 v[4:7], v[4:7], v[0:3], 0
	v_mfma_f32_16x16x32_bf16 v[52:55], v[8:11], v[64:67], v[4:7]
	ds_read_b128 v[8:11], v79 offset:6976
	s_nop 5
	ds_read_b128 v[4:7], v79 offset:6912
	s_waitcnt lgkmcnt(0)
	v_mfma_f32_16x16x32_bf16 v[4:7], v[4:7], v[0:3], 0
	v_mfma_f32_16x16x32_bf16 v[48:51], v[8:11], v[64:67], v[4:7]
	ds_read_b128 v[8:11], v79 offset:9280
	s_nop 5
	ds_read_b128 v[4:7], v79 offset:9216
	s_waitcnt lgkmcnt(0)
	v_mfma_f32_16x16x32_bf16 v[4:7], v[4:7], v[0:3], 0
	v_mfma_f32_16x16x32_bf16 v[44:47], v[8:11], v[64:67], v[4:7]
	ds_read_b128 v[8:11], v79 offset:11584
	s_nop 5
	ds_read_b128 v[4:7], v79 offset:11520
	s_waitcnt lgkmcnt(0)
	v_mfma_f32_16x16x32_bf16 v[4:7], v[4:7], v[0:3], 0
	v_mfma_f32_16x16x32_bf16 v[40:43], v[8:11], v[64:67], v[4:7]
	ds_read_b128 v[8:11], v79 offset:13888
	s_nop 5
	ds_read_b128 v[4:7], v79 offset:13824
	s_waitcnt lgkmcnt(0)
	v_mfma_f32_16x16x32_bf16 v[4:7], v[4:7], v[0:3], 0
	v_mfma_f32_16x16x32_bf16 v[36:39], v[8:11], v[64:67], v[4:7]
	ds_read_b128 v[8:11], v79 offset:16192
	s_nop 5
	ds_read_b128 v[4:7], v79 offset:16128
	s_waitcnt lgkmcnt(0)
	v_mfma_f32_16x16x32_bf16 v[4:7], v[4:7], v[0:3], 0
	v_mfma_f32_16x16x32_bf16 v[32:35], v[8:11], v[64:67], v[4:7]
	ds_read_b128 v[8:11], v79 offset:18496
	s_nop 5
	ds_read_b128 v[4:7], v79 offset:18432
	s_waitcnt lgkmcnt(0)
	v_mfma_f32_16x16x32_bf16 v[4:7], v[4:7], v[0:3], 0
	v_mfma_f32_16x16x32_bf16 v[28:31], v[8:11], v[64:67], v[4:7]
	ds_read_b128 v[8:11], v79 offset:20800
	s_nop 5
	ds_read_b128 v[4:7], v79 offset:20736
	s_waitcnt lgkmcnt(0)
	v_mfma_f32_16x16x32_bf16 v[4:7], v[4:7], v[0:3], 0
	v_mfma_f32_16x16x32_bf16 v[24:27], v[8:11], v[64:67], v[4:7]
	ds_read_b128 v[8:11], v79 offset:23104
	s_nop 5
	ds_read_b128 v[4:7], v79 offset:23040
	s_waitcnt lgkmcnt(0)
	v_mfma_f32_16x16x32_bf16 v[4:7], v[4:7], v[0:3], 0
	v_mfma_f32_16x16x32_bf16 v[20:23], v[8:11], v[64:67], v[4:7]
	ds_read_b128 v[8:11], v79 offset:25408
	s_nop 5
	ds_read_b128 v[4:7], v79 offset:25344
	s_waitcnt lgkmcnt(0)
	v_mfma_f32_16x16x32_bf16 v[4:7], v[4:7], v[0:3], 0
	v_mfma_f32_16x16x32_bf16 v[16:19], v[8:11], v[64:67], v[4:7]
	ds_read_b128 v[8:11], v79 offset:27712
	s_nop 5
	ds_read_b128 v[4:7], v79 offset:27648
	s_waitcnt lgkmcnt(0)
	v_mfma_f32_16x16x32_bf16 v[4:7], v[4:7], v[0:3], 0
	v_mfma_f32_16x16x32_bf16 v[12:15], v[8:11], v[64:67], v[4:7]
	ds_read_b128 v[8:11], v79 offset:30016
	s_nop 5
	ds_read_b128 v[4:7], v79 offset:29952
	s_waitcnt lgkmcnt(0)
	v_mfma_f32_16x16x32_bf16 v[4:7], v[4:7], v[0:3], 0
	v_mfma_f32_16x16x32_bf16 v[8:11], v[8:11], v[64:67], v[4:7]
	s_nop 6
	ds_read_b128 v[4:7], v79 offset:32256
	s_waitcnt lgkmcnt(0)
	v_mfma_f32_16x16x32_bf16 v[4:7], v[4:7], v[0:3], 0
	v_mfma_f32_16x16x32_bf16 v[4:7], v[74:77], v[64:67], v[4:7]
	ds_read_b128 v[74:77], v79 offset:34560
	s_waitcnt lgkmcnt(0)
	v_mfma_f32_16x16x32_bf16 v[0:3], v[74:77], v[0:3], 0
	ds_read_b128 v[74:77], v79 offset:34624
	s_waitcnt lgkmcnt(0)
	v_mfma_f32_16x16x32_bf16 v[0:3], v[74:77], v[64:67], v[0:3]
	v_mul_f32_e32 v64, 0x3e000000, v60
	v_mul_f32_e32 v65, 0x3e000000, v61
	s_mov_b32 s2, 0xff61b1e6
	v_max3_f32 v64, v64, s2, v65
	v_mul_f32_e32 v65, 0x3e000000, v62
	v_mul_f32_e32 v66, 0x3e000000, v63
	v_max3_f32 v64, v64, v65, v66
	v_mul_f32_e32 v65, 0x3e000000, v56
	v_mul_f32_e32 v66, 0x3e000000, v57
	v_max3_f32 v64, v64, v65, v66
	v_mul_f32_e32 v65, 0x3e000000, v58
	v_mul_f32_e32 v66, 0x3e000000, v59
	v_max3_f32 v64, v64, v65, v66
	v_mul_f32_e32 v65, 0x3e000000, v52
	v_mul_f32_e32 v66, 0x3e000000, v53
	v_max3_f32 v64, v64, v65, v66
	v_mul_f32_e32 v65, 0x3e000000, v54
	v_mul_f32_e32 v66, 0x3e000000, v55
	v_max3_f32 v64, v64, v65, v66
	v_mul_f32_e32 v65, 0x3e000000, v48
	v_mul_f32_e32 v66, 0x3e000000, v49
	v_max3_f32 v64, v64, v65, v66
	v_mul_f32_e32 v65, 0x3e000000, v50
	v_mul_f32_e32 v66, 0x3e000000, v51
	v_max3_f32 v64, v64, v65, v66
	v_mul_f32_e32 v65, 0x3e000000, v44
	v_mul_f32_e32 v66, 0x3e000000, v45
	v_max3_f32 v64, v64, v65, v66
	v_mul_f32_e32 v65, 0x3e000000, v46
	v_mul_f32_e32 v66, 0x3e000000, v47
	v_max3_f32 v64, v64, v65, v66
	v_mul_f32_e32 v65, 0x3e000000, v40
	v_mul_f32_e32 v66, 0x3e000000, v41
	v_max3_f32 v64, v64, v65, v66
	v_mul_f32_e32 v65, 0x3e000000, v42
	v_mul_f32_e32 v66, 0x3e000000, v43
	v_max3_f32 v64, v64, v65, v66
	v_mul_f32_e32 v65, 0x3e000000, v36
	v_mul_f32_e32 v66, 0x3e000000, v37
	v_max3_f32 v64, v64, v65, v66
	v_mul_f32_e32 v65, 0x3e000000, v38
	v_mul_f32_e32 v66, 0x3e000000, v39
	v_max3_f32 v64, v64, v65, v66
	v_mul_f32_e32 v65, 0x3e000000, v32
	v_mul_f32_e32 v66, 0x3e000000, v33
	v_max3_f32 v64, v64, v65, v66
	v_mul_f32_e32 v65, 0x3e000000, v34
	v_mul_f32_e32 v66, 0x3e000000, v35
	v_max3_f32 v64, v64, v65, v66
	v_mul_f32_e32 v65, 0x3e000000, v28
	v_mul_f32_e32 v66, 0x3e000000, v29
	v_max3_f32 v64, v64, v65, v66
	v_mul_f32_e32 v65, 0x3e000000, v30
	v_mul_f32_e32 v66, 0x3e000000, v31
	v_max3_f32 v64, v64, v65, v66
	v_mul_f32_e32 v65, 0x3e000000, v24
	v_mul_f32_e32 v66, 0x3e000000, v25
	v_max3_f32 v64, v64, v65, v66
	v_mul_f32_e32 v65, 0x3e000000, v26
	v_mul_f32_e32 v66, 0x3e000000, v27
	v_max3_f32 v64, v64, v65, v66
	v_mul_f32_e32 v65, 0x3e000000, v20
	v_mul_f32_e32 v66, 0x3e000000, v21
	v_max3_f32 v64, v64, v65, v66
	v_mul_f32_e32 v65, 0x3e000000, v22
	v_mul_f32_e32 v66, 0x3e000000, v23
	v_max3_f32 v64, v64, v65, v66
	v_mul_f32_e32 v65, 0x3e000000, v16
	v_mul_f32_e32 v66, 0x3e000000, v17
	v_max3_f32 v64, v64, v65, v66
	v_mul_f32_e32 v65, 0x3e000000, v18
	v_mul_f32_e32 v66, 0x3e000000, v19
	v_max3_f32 v64, v64, v65, v66
	v_mul_f32_e32 v65, 0x3e000000, v12
	v_mul_f32_e32 v66, 0x3e000000, v13
	v_max3_f32 v64, v64, v65, v66
	v_mul_f32_e32 v65, 0x3e000000, v14
	v_mul_f32_e32 v66, 0x3e000000, v15
	v_max3_f32 v64, v64, v65, v66
	v_mul_f32_e32 v65, 0x3e000000, v8
	v_mul_f32_e32 v66, 0x3e000000, v9
	v_max3_f32 v64, v64, v65, v66
	v_mul_f32_e32 v65, 0x3e000000, v10
	v_mul_f32_e32 v66, 0x3e000000, v11
	v_max3_f32 v64, v64, v65, v66
	v_mul_f32_e32 v65, 0x3e000000, v4
	v_mul_f32_e32 v66, 0x3e000000, v5
	v_max3_f32 v64, v64, v65, v66
	v_mul_f32_e32 v65, 0x3e000000, v6
	v_mul_f32_e32 v66, 0x3e000000, v7
	v_max3_f32 v64, v64, v65, v66
	v_mul_f32_e32 v65, 0x3e000000, v0
	v_mul_f32_e32 v66, 0x3e000000, v1
	v_max3_f32 v64, v64, v65, v66
	v_mul_f32_e32 v65, 0x3e000000, v2
	v_mul_f32_e32 v66, 0x3e000000, v3
	v_max3_f32 v64, v64, v65, v66
	v_lshlrev_b32_e32 v74, 2, v78
	ds_bpermute_b32 v65, v74, v64
	s_mov_b32 s2, 0x3e000000
	v_sub_u32_e32 v72, v72, v70
	s_waitcnt lgkmcnt(0)
	v_max_f32_e32 v65, v65, v65
	v_max_f32_e32 v64, v64, v65
	ds_bpermute_b32 v65, v73, v64
	s_waitcnt lgkmcnt(0)
	v_max_f32_e32 v65, v65, v65
	v_max_f32_e32 v75, v64, v65
	v_fma_f32 v60, v60, s2, -v75
	v_fma_f32 v61, v61, s2, -v75
	v_mul_f32_e32 v60, 0x3fb8aa3b, v60
	v_mul_f32_e32 v61, 0x3fb8aa3b, v61
	v_exp_f32_e32 v60, v60
	v_exp_f32_e32 v64, v61
	v_fma_f32 v61, v62, s2, -v75
	v_mul_f32_e32 v61, 0x3fb8aa3b, v61
	v_exp_f32_e32 v61, v61
	v_add_f32_e32 v65, 0, v60
	v_fma_f32 v63, v63, s2, -v75
	v_add_f32_e32 v65, v64, v65
	v_mul_f32_e32 v63, 0x3fb8aa3b, v63
	v_add_f32_e32 v62, v61, v65
	v_exp_f32_e32 v65, v63
	v_fma_f32 v56, v56, s2, -v75
	v_mul_f32_e32 v56, 0x3fb8aa3b, v56
	v_fma_f32 v57, v57, s2, -v75
	v_add_f32_e32 v63, v65, v62
	v_exp_f32_e32 v62, v56
	v_mul_f32_e32 v57, 0x3fb8aa3b, v57
	v_exp_f32_e32 v66, v57
	v_fma_f32 v57, v58, s2, -v75
	v_mul_f32_e32 v57, 0x3fb8aa3b, v57
	v_add_f32_e32 v56, v62, v63
	v_exp_f32_e32 v63, v57
	v_fma_f32 v57, v59, s2, -v75
	v_mul_f32_e32 v57, 0x3fb8aa3b, v57
	v_fma_f32 v52, v52, s2, -v75
	v_exp_f32_e32 v67, v57
	v_mul_f32_e32 v52, 0x3fb8aa3b, v52
	v_exp_f32_e32 v52, v52
	v_add_f32_e32 v56, v66, v56
	v_add_f32_e32 v56, v63, v56
	v_fma_f32 v53, v53, s2, -v75
	v_add_f32_e32 v56, v67, v56
	v_mul_f32_e32 v53, 0x3fb8aa3b, v53
	v_add_f32_e32 v57, v52, v56
	v_exp_f32_e32 v56, v53
	v_fma_f32 v53, v54, s2, -v75
	v_mul_f32_e32 v53, 0x3fb8aa3b, v53
	v_exp_f32_e32 v53, v53
	v_fma_f32 v55, v55, s2, -v75
	v_add_f32_e32 v57, v56, v57
	v_mul_f32_e32 v55, 0x3fb8aa3b, v55
	v_add_f32_e32 v54, v53, v57
	v_exp_f32_e32 v57, v55
	v_fma_f32 v48, v48, s2, -v75
	v_mul_f32_e32 v48, 0x3fb8aa3b, v48
	v_fma_f32 v49, v49, s2, -v75
	v_add_f32_e32 v55, v57, v54
	v_exp_f32_e32 v54, v48
	v_mul_f32_e32 v49, 0x3fb8aa3b, v49
	v_exp_f32_e32 v58, v49
	v_fma_f32 v49, v50, s2, -v75
	v_mul_f32_e32 v49, 0x3fb8aa3b, v49
	v_add_f32_e32 v48, v54, v55
	v_exp_f32_e32 v55, v49
	v_fma_f32 v49, v51, s2, -v75
	v_mul_f32_e32 v49, 0x3fb8aa3b, v49
	v_fma_f32 v44, v44, s2, -v75
	v_exp_f32_e32 v59, v49
	v_mul_f32_e32 v44, 0x3fb8aa3b, v44
	v_exp_f32_e32 v44, v44
	v_add_f32_e32 v48, v58, v48
	v_add_f32_e32 v48, v55, v48
	v_fma_f32 v45, v45, s2, -v75
	v_add_f32_e32 v48, v59, v48
	v_mul_f32_e32 v45, 0x3fb8aa3b, v45
	v_add_f32_e32 v49, v44, v48
	v_exp_f32_e32 v48, v45
	v_fma_f32 v45, v46, s2, -v75
	v_mul_f32_e32 v45, 0x3fb8aa3b, v45
	v_exp_f32_e32 v45, v45
	v_fma_f32 v47, v47, s2, -v75
	v_add_f32_e32 v49, v48, v49
	v_mul_f32_e32 v47, 0x3fb8aa3b, v47
	v_add_f32_e32 v46, v45, v49
	v_exp_f32_e32 v49, v47
	v_fma_f32 v40, v40, s2, -v75
	v_mul_f32_e32 v40, 0x3fb8aa3b, v40
	v_fma_f32 v41, v41, s2, -v75
	v_add_f32_e32 v47, v49, v46
	v_exp_f32_e32 v46, v40
	v_mul_f32_e32 v41, 0x3fb8aa3b, v41
	v_exp_f32_e32 v50, v41
	v_fma_f32 v41, v42, s2, -v75
	v_mul_f32_e32 v41, 0x3fb8aa3b, v41
	v_add_f32_e32 v40, v46, v47
	v_exp_f32_e32 v47, v41
	v_fma_f32 v41, v43, s2, -v75
	v_mul_f32_e32 v41, 0x3fb8aa3b, v41
	v_fma_f32 v36, v36, s2, -v75
	v_exp_f32_e32 v51, v41
	v_mul_f32_e32 v36, 0x3fb8aa3b, v36
	v_exp_f32_e32 v36, v36
	v_add_f32_e32 v40, v50, v40
	v_add_f32_e32 v40, v47, v40
	v_fma_f32 v37, v37, s2, -v75
	v_add_f32_e32 v40, v51, v40
	v_mul_f32_e32 v37, 0x3fb8aa3b, v37
	v_add_f32_e32 v41, v36, v40
	v_exp_f32_e32 v40, v37
	v_fma_f32 v37, v38, s2, -v75
	v_mul_f32_e32 v37, 0x3fb8aa3b, v37
	v_exp_f32_e32 v37, v37
	v_fma_f32 v39, v39, s2, -v75
	v_add_f32_e32 v41, v40, v41
	v_mul_f32_e32 v39, 0x3fb8aa3b, v39
	v_add_f32_e32 v38, v37, v41
	v_exp_f32_e32 v41, v39
	v_fma_f32 v32, v32, s2, -v75
	v_mul_f32_e32 v32, 0x3fb8aa3b, v32
	v_fma_f32 v33, v33, s2, -v75
	v_add_f32_e32 v39, v41, v38
	v_exp_f32_e32 v38, v32
	v_mul_f32_e32 v33, 0x3fb8aa3b, v33
	v_exp_f32_e32 v42, v33
	v_fma_f32 v33, v34, s2, -v75
	v_mul_f32_e32 v33, 0x3fb8aa3b, v33
	v_add_f32_e32 v32, v38, v39
	v_exp_f32_e32 v39, v33
	v_fma_f32 v33, v35, s2, -v75
	v_mul_f32_e32 v33, 0x3fb8aa3b, v33
	v_fma_f32 v28, v28, s2, -v75
	v_exp_f32_e32 v43, v33
	v_mul_f32_e32 v28, 0x3fb8aa3b, v28
	v_exp_f32_e32 v28, v28
	v_add_f32_e32 v32, v42, v32
	v_add_f32_e32 v32, v39, v32
	v_fma_f32 v29, v29, s2, -v75
	v_add_f32_e32 v32, v43, v32
	v_mul_f32_e32 v29, 0x3fb8aa3b, v29
	v_add_f32_e32 v33, v28, v32
	v_exp_f32_e32 v32, v29
	v_fma_f32 v29, v30, s2, -v75
	v_mul_f32_e32 v29, 0x3fb8aa3b, v29
	v_exp_f32_e32 v29, v29
	v_fma_f32 v31, v31, s2, -v75
	v_add_f32_e32 v33, v32, v33
	v_mul_f32_e32 v31, 0x3fb8aa3b, v31
	v_add_f32_e32 v30, v29, v33
	v_exp_f32_e32 v33, v31
	v_fma_f32 v24, v24, s2, -v75
	v_mul_f32_e32 v24, 0x3fb8aa3b, v24
	v_fma_f32 v25, v25, s2, -v75
	v_add_f32_e32 v31, v33, v30
	v_exp_f32_e32 v30, v24
	v_mul_f32_e32 v25, 0x3fb8aa3b, v25
	v_exp_f32_e32 v34, v25
	v_fma_f32 v25, v26, s2, -v75
	v_mul_f32_e32 v25, 0x3fb8aa3b, v25
	v_add_f32_e32 v24, v30, v31
	v_exp_f32_e32 v31, v25
	v_fma_f32 v25, v27, s2, -v75
	v_mul_f32_e32 v25, 0x3fb8aa3b, v25
	v_fma_f32 v20, v20, s2, -v75
	v_exp_f32_e32 v35, v25
	v_mul_f32_e32 v20, 0x3fb8aa3b, v20
	v_exp_f32_e32 v20, v20
	v_add_f32_e32 v24, v34, v24
	v_add_f32_e32 v24, v31, v24
	v_fma_f32 v21, v21, s2, -v75
	v_add_f32_e32 v24, v35, v24
	v_mul_f32_e32 v21, 0x3fb8aa3b, v21
	v_add_f32_e32 v25, v20, v24
	v_exp_f32_e32 v24, v21
	v_fma_f32 v21, v22, s2, -v75
	v_mul_f32_e32 v21, 0x3fb8aa3b, v21
	v_exp_f32_e32 v21, v21
	v_fma_f32 v23, v23, s2, -v75
	v_add_f32_e32 v25, v24, v25
	v_mul_f32_e32 v23, 0x3fb8aa3b, v23
	v_add_f32_e32 v22, v21, v25
	v_exp_f32_e32 v25, v23
	v_fma_f32 v16, v16, s2, -v75
	v_mul_f32_e32 v16, 0x3fb8aa3b, v16
	v_fma_f32 v17, v17, s2, -v75
	v_add_f32_e32 v23, v25, v22
	v_exp_f32_e32 v22, v16
	v_mul_f32_e32 v17, 0x3fb8aa3b, v17
	v_exp_f32_e32 v26, v17
	v_fma_f32 v17, v18, s2, -v75
	v_mul_f32_e32 v17, 0x3fb8aa3b, v17
	v_add_f32_e32 v16, v22, v23
	v_exp_f32_e32 v23, v17
	v_fma_f32 v17, v19, s2, -v75
	v_mul_f32_e32 v17, 0x3fb8aa3b, v17
	v_fma_f32 v12, v12, s2, -v75
	v_exp_f32_e32 v27, v17
	v_mul_f32_e32 v12, 0x3fb8aa3b, v12
	v_exp_f32_e32 v12, v12
	v_add_f32_e32 v16, v26, v16
	v_add_f32_e32 v16, v23, v16
	v_fma_f32 v13, v13, s2, -v75
	v_add_f32_e32 v16, v27, v16
	v_mul_f32_e32 v13, 0x3fb8aa3b, v13
	v_add_f32_e32 v17, v12, v16
	v_exp_f32_e32 v16, v13
	v_fma_f32 v13, v14, s2, -v75
	v_mul_f32_e32 v13, 0x3fb8aa3b, v13
	v_exp_f32_e32 v13, v13
	v_fma_f32 v15, v15, s2, -v75
	v_add_f32_e32 v17, v16, v17
	v_mul_f32_e32 v15, 0x3fb8aa3b, v15
	v_add_f32_e32 v14, v13, v17
	v_exp_f32_e32 v17, v15
	v_fma_f32 v8, v8, s2, -v75
	v_mul_f32_e32 v8, 0x3fb8aa3b, v8
	v_fma_f32 v9, v9, s2, -v75
	v_add_f32_e32 v15, v17, v14
	v_exp_f32_e32 v14, v8
	v_mul_f32_e32 v9, 0x3fb8aa3b, v9
	v_exp_f32_e32 v18, v9
	v_fma_f32 v9, v10, s2, -v75
	v_mul_f32_e32 v9, 0x3fb8aa3b, v9
	v_add_f32_e32 v8, v14, v15
	v_exp_f32_e32 v15, v9
	v_fma_f32 v9, v11, s2, -v75
	v_mul_f32_e32 v9, 0x3fb8aa3b, v9
	v_fma_f32 v4, v4, s2, -v75
	v_exp_f32_e32 v19, v9
	v_mul_f32_e32 v4, 0x3fb8aa3b, v4
	v_exp_f32_e32 v4, v4
	v_add_f32_e32 v8, v18, v8
	v_add_f32_e32 v8, v15, v8
	v_fma_f32 v5, v5, s2, -v75
	v_add_f32_e32 v8, v19, v8
	v_mul_f32_e32 v5, 0x3fb8aa3b, v5
	v_add_f32_e32 v9, v4, v8
	v_exp_f32_e32 v8, v5
	v_fma_f32 v5, v6, s2, -v75
	v_mul_f32_e32 v5, 0x3fb8aa3b, v5
	v_exp_f32_e32 v5, v5
	v_fma_f32 v7, v7, s2, -v75
	v_add_f32_e32 v9, v8, v9
	v_mul_f32_e32 v7, 0x3fb8aa3b, v7
	v_fma_f32 v0, v0, s2, -v75
	v_add_f32_e32 v6, v5, v9
	v_exp_f32_e32 v9, v7
	v_mul_f32_e32 v0, 0x3fb8aa3b, v0
	v_exp_f32_e32 v0, v0
	v_fma_f32 v1, v1, s2, -v75
	v_add_f32_e32 v6, v9, v6
	v_mul_f32_e32 v1, 0x3fb8aa3b, v1
	v_add_f32_e32 v7, v0, v6
	v_exp_f32_e32 v6, v1
	v_fma_f32 v1, v2, s2, -v75
	v_mul_f32_e32 v1, 0x3fb8aa3b, v1
	v_exp_f32_e32 v1, v1
	v_fma_f32 v3, v3, s2, -v75
	v_add_f32_e32 v7, v6, v7
	v_mul_f32_e32 v3, 0x3fb8aa3b, v3
	v_add_f32_e32 v2, v1, v7
	v_exp_f32_e32 v7, v3
	s_nop 0
	v_add_f32_e32 v2, v7, v2
	ds_bpermute_b32 v3, v74, v2
	s_waitcnt lgkmcnt(0)
	v_add_f32_e32 v2, v2, v3
	ds_bpermute_b32 v3, v73, v2
	s_waitcnt lgkmcnt(0)
	v_add_f32_e32 v2, v2, v3
	v_div_scale_f32 v3, s[2:3], v2, v2, 1.0
	v_rcp_f32_e32 v10, v3
	v_div_scale_f32 v11, vcc, 1.0, v2, 1.0
	s_movk_i32 s2, 0x210
	v_fma_f32 v73, -v3, v10, 1.0
	v_fmac_f32_e32 v10, v73, v10
	v_mul_f32_e32 v73, v11, v10
	v_fma_f32 v74, -v3, v73, v11
	v_fmac_f32_e32 v73, v74, v10
	v_fma_f32 v3, -v3, v73, v11
	v_div_fmas_f32 v3, v3, v10, v73
	v_div_fixup_f32 v2, v3, v2, 1.0
	v_pk_mul_f32 v[10:11], v[60:61], v[2:3] op_sel_hi:[1,0]
	v_pk_mul_f32 v[60:61], v[64:65], v[2:3] op_sel_hi:[1,0]
	v_pk_mul_f32 v[64:65], v[66:67], v[2:3] op_sel_hi:[1,0]
	v_pk_mul_f32 v[62:63], v[62:63], v[2:3] op_sel_hi:[1,0]
	v_bfe_u32 v3, v65, 16, 1
	v_bfe_u32 v66, v64, 16, 1
	v_bfe_u32 v67, v61, 16, 1
	v_bfe_u32 v73, v60, 16, 1
	v_add3_u32 v65, v65, v3, s33
	v_bfe_u32 v3, v10, 16, 1
	v_mad_u32_u24 v71, v71, s2, v72
	v_add3_u32 v73, v60, v73, s33
	v_add3_u32 v74, v61, v67, s33
	v_add3_u32 v64, v64, v66, s33
	v_bfe_u32 v60, v11, 16, 1
	v_bfe_u32 v61, v62, 16, 1
	v_bfe_u32 v66, v63, 16, 1
	v_add3_u32 v10, v10, v3, s33
	v_add_u32_e32 v3, 0x9000, v71
	v_add3_u32 v66, v63, v66, s33
	v_add3_u32 v67, v62, v61, s33
	v_add3_u32 v11, v11, v60, s33
	ds_read2_b64 v[60:63], v3 offset1:4
	v_lshrrev_b32_e32 v10, 16, v10
	v_lshrrev_b32_e32 v11, 16, v11
	v_lshrrev_b32_e32 v72, 16, v67
	v_lshrrev_b32_e32 v66, 16, v66
	v_and_or_b32 v67, v65, s29, v66
	v_and_or_b32 v66, v64, s29, v72
	v_and_or_b32 v65, v74, s29, v11
	v_and_or_b32 v64, v73, s29, v10
	v_add_u32_e32 v10, 0xb000, v71
	s_waitcnt lgkmcnt(0)
	v_mfma_f32_16x16x32_bf16 v[72:75], v[60:63], v[64:67], 0
	ds_read2_b64 v[60:63], v10 offset0:32 offset1:36
	s_waitcnt lgkmcnt(0)
	v_mfma_f32_16x16x32_bf16 v[76:79], v[60:63], v[64:67], 0
	v_add_u32_e32 v60, 0xd000, v71
	v_add_u32_e32 v61, 0xf000, v71
	ds_read2_b64 v[82:85], v60 offset0:64 offset1:68
	ds_read2_b64 v[86:89], v61 offset0:96 offset1:100
	s_waitcnt lgkmcnt(1)
	v_mfma_f32_16x16x32_bf16 v[82:85], v[82:85], v[64:67], 0
	s_waitcnt lgkmcnt(0)
	v_mfma_f32_16x16x32_bf16 v[62:65], v[86:89], v[64:67], 0
	ds_read2_b64 v[204:207], v3 offset0:8 offset1:12
	ds_read2_b64 v[208:211], v10 offset0:40 offset1:44
	ds_read2_b64 v[212:215], v60 offset0:72 offset1:76
	ds_read2_b64 v[216:219], v61 offset0:104 offset1:108
	v_mul_f32_e64 v56, v56, v2
	v_mul_f32_e64 v57, v57, v2
	v_pk_mul_f32 v[58:59], v[58:59], v[2:3] op_sel_hi:[1,0]
	v_pk_mul_f32 v[52:53], v[52:53], v[2:3] op_sel_hi:[1,0]
	v_pk_mul_f32 v[54:55], v[54:55], v[2:3] op_sel_hi:[1,0]
	v_bfe_u32 v11, v59, 16, 1
	v_bfe_u32 v66, v58, 16, 1
	v_bfe_u32 v67, v57, 16, 1
	v_bfe_u32 v71, v56, 16, 1
	v_add3_u32 v56, v56, v71, s33
	v_add3_u32 v57, v57, v67, s33
	v_add3_u32 v58, v58, v66, s33
	v_add3_u32 v11, v59, v11, s33
	v_bfe_u32 v59, v52, 16, 1
	v_bfe_u32 v66, v53, 16, 1
	v_bfe_u32 v67, v54, 16, 1
	v_bfe_u32 v71, v55, 16, 1
	v_add3_u32 v71, v55, v71, s33
	v_add3_u32 v67, v54, v67, s33
	v_add3_u32 v66, v53, v66, s33
	v_add3_u32 v59, v52, v59, s33
	v_lshrrev_b32_e32 v81, 16, v59
	v_lshrrev_b32_e32 v66, 16, v66
	v_lshrrev_b32_e32 v67, 16, v67
	v_lshrrev_b32_e32 v59, 16, v71
	v_and_or_b32 v59, v11, s29, v59
	v_and_or_b32 v58, v58, s29, v67
	v_and_or_b32 v57, v57, s29, v66
	v_and_or_b32 v56, v56, s29, v81
	s_waitcnt lgkmcnt(3)
	s_nop 1
	v_mfma_f32_16x16x32_bf16 v[52:55], v[204:207], v[56:59], v[72:75]
	s_waitcnt lgkmcnt(2)
	v_mfma_f32_16x16x32_bf16 v[72:75], v[208:211], v[56:59], v[76:79]
	s_waitcnt lgkmcnt(1)
	v_mfma_f32_16x16x32_bf16 v[76:79], v[212:215], v[56:59], v[82:85]
	s_waitcnt lgkmcnt(0)
	v_mfma_f32_16x16x32_bf16 v[56:59], v[216:219], v[56:59], v[62:65]
	ds_read2_b64 v[204:207], v3 offset0:16 offset1:20
	ds_read2_b64 v[208:211], v10 offset0:48 offset1:52
	ds_read2_b64 v[212:215], v60 offset0:80 offset1:84
	ds_read2_b64 v[216:219], v61 offset0:112 offset1:116
	v_mul_f32_e64 v48, v48, v2
	v_mul_f32_e64 v49, v49, v2
	v_pk_mul_f32 v[50:51], v[50:51], v[2:3] op_sel_hi:[1,0]
	v_pk_mul_f32 v[44:45], v[44:45], v[2:3] op_sel_hi:[1,0]
	v_pk_mul_f32 v[46:47], v[46:47], v[2:3] op_sel_hi:[1,0]
	v_bfe_u32 v11, v51, 16, 1
	v_bfe_u32 v62, v50, 16, 1
	v_bfe_u32 v63, v49, 16, 1
	v_bfe_u32 v64, v48, 16, 1
	v_add3_u32 v48, v48, v64, s33
	v_add3_u32 v49, v49, v63, s33
	v_add3_u32 v50, v50, v62, s33
	v_add3_u32 v11, v51, v11, s33
	v_bfe_u32 v51, v44, 16, 1
	v_bfe_u32 v62, v45, 16, 1
	v_bfe_u32 v63, v46, 16, 1
	v_bfe_u32 v64, v47, 16, 1
	v_add3_u32 v64, v47, v64, s33
	v_add3_u32 v63, v46, v63, s33
	v_add3_u32 v62, v45, v62, s33
	v_add3_u32 v51, v44, v51, s33
	v_lshrrev_b32_e32 v65, 16, v51
	v_lshrrev_b32_e32 v62, 16, v62
	v_lshrrev_b32_e32 v63, 16, v63
	v_lshrrev_b32_e32 v51, 16, v64
	v_and_or_b32 v51, v11, s29, v51
	v_and_or_b32 v50, v50, s29, v63
	v_and_or_b32 v49, v49, s29, v62
	v_and_or_b32 v48, v48, s29, v65
	s_waitcnt lgkmcnt(3)
	s_nop 1
	v_mfma_f32_16x16x32_bf16 v[44:47], v[204:207], v[48:51], v[52:55]
	s_waitcnt lgkmcnt(2)
	v_mfma_f32_16x16x32_bf16 v[52:55], v[208:211], v[48:51], v[72:75]
	s_waitcnt lgkmcnt(1)
	v_mfma_f32_16x16x32_bf16 v[62:65], v[212:215], v[48:51], v[76:79]
	s_waitcnt lgkmcnt(0)
	v_mfma_f32_16x16x32_bf16 v[48:51], v[216:219], v[48:51], v[56:59]
	ds_read2_b64 v[204:207], v3 offset0:24 offset1:28
	ds_read2_b64 v[208:211], v10 offset0:56 offset1:60
	ds_read2_b64 v[212:215], v60 offset0:88 offset1:92
	ds_read2_b64 v[216:219], v61 offset0:120 offset1:124
	v_mul_f32_e64 v40, v40, v2
	v_mul_f32_e64 v41, v41, v2
	v_pk_mul_f32 v[42:43], v[42:43], v[2:3] op_sel_hi:[1,0]
	v_pk_mul_f32 v[36:37], v[36:37], v[2:3] op_sel_hi:[1,0]
	v_pk_mul_f32 v[38:39], v[38:39], v[2:3] op_sel_hi:[1,0]
	v_bfe_u32 v11, v43, 16, 1
	v_bfe_u32 v56, v42, 16, 1
	v_bfe_u32 v57, v41, 16, 1
	v_bfe_u32 v58, v40, 16, 1
	v_add3_u32 v40, v40, v58, s33
	v_add3_u32 v41, v41, v57, s33
	v_add3_u32 v42, v42, v56, s33
	v_add3_u32 v11, v43, v11, s33
	v_bfe_u32 v43, v36, 16, 1
	v_bfe_u32 v56, v37, 16, 1
	v_bfe_u32 v57, v38, 16, 1
	v_bfe_u32 v58, v39, 16, 1
	v_add3_u32 v58, v39, v58, s33
	v_add3_u32 v57, v38, v57, s33
	v_add3_u32 v56, v37, v56, s33
	v_add3_u32 v43, v36, v43, s33
	v_lshrrev_b32_e32 v59, 16, v43
	v_lshrrev_b32_e32 v56, 16, v56
	v_lshrrev_b32_e32 v57, 16, v57
	v_lshrrev_b32_e32 v43, 16, v58
	v_and_or_b32 v43, v11, s29, v43
	v_and_or_b32 v42, v42, s29, v57
	v_and_or_b32 v41, v41, s29, v56
	v_and_or_b32 v40, v40, s29, v59
	s_waitcnt lgkmcnt(3)
	s_nop 1
	v_mfma_f32_16x16x32_bf16 v[36:39], v[204:207], v[40:43], v[44:47]
	s_waitcnt lgkmcnt(2)
	v_mfma_f32_16x16x32_bf16 v[44:47], v[208:211], v[40:43], v[52:55]
	s_waitcnt lgkmcnt(1)
	v_mfma_f32_16x16x32_bf16 v[52:55], v[212:215], v[40:43], v[62:65]
	s_waitcnt lgkmcnt(0)
	v_mfma_f32_16x16x32_bf16 v[40:43], v[216:219], v[40:43], v[48:51]
	ds_read2_b64 v[204:207], v3 offset0:32 offset1:36
	ds_read2_b64 v[208:211], v10 offset0:64 offset1:68
	ds_read2_b64 v[212:215], v60 offset0:96 offset1:100
	ds_read2_b64 v[216:219], v61 offset0:128 offset1:132
	v_mul_f32_e64 v32, v32, v2
	v_mul_f32_e64 v33, v33, v2
	v_pk_mul_f32 v[34:35], v[34:35], v[2:3] op_sel_hi:[1,0]
	v_pk_mul_f32 v[28:29], v[28:29], v[2:3] op_sel_hi:[1,0]
	v_pk_mul_f32 v[30:31], v[30:31], v[2:3] op_sel_hi:[1,0]
	v_bfe_u32 v11, v35, 16, 1
	v_bfe_u32 v48, v34, 16, 1
	v_bfe_u32 v49, v33, 16, 1
	v_bfe_u32 v50, v32, 16, 1
	v_add3_u32 v32, v32, v50, s33
	v_add3_u32 v33, v33, v49, s33
	v_add3_u32 v34, v34, v48, s33
	v_add3_u32 v11, v35, v11, s33
	v_bfe_u32 v35, v28, 16, 1
	v_bfe_u32 v48, v29, 16, 1
	v_bfe_u32 v49, v30, 16, 1
	v_bfe_u32 v50, v31, 16, 1
	v_add3_u32 v50, v31, v50, s33
	v_add3_u32 v49, v30, v49, s33
	v_add3_u32 v48, v29, v48, s33
	v_add3_u32 v35, v28, v35, s33
	v_lshrrev_b32_e32 v51, 16, v35
	v_lshrrev_b32_e32 v48, 16, v48
	v_lshrrev_b32_e32 v49, 16, v49
	v_lshrrev_b32_e32 v35, 16, v50
	v_and_or_b32 v35, v11, s29, v35
	v_and_or_b32 v34, v34, s29, v49
	v_and_or_b32 v33, v33, s29, v48
	v_and_or_b32 v32, v32, s29, v51
	s_waitcnt lgkmcnt(3)
	s_nop 1
	v_mfma_f32_16x16x32_bf16 v[28:31], v[204:207], v[32:35], v[36:39]
	s_waitcnt lgkmcnt(2)
	v_mfma_f32_16x16x32_bf16 v[36:39], v[208:211], v[32:35], v[44:47]
	s_waitcnt lgkmcnt(1)
	v_mfma_f32_16x16x32_bf16 v[44:47], v[212:215], v[32:35], v[52:55]
	s_waitcnt lgkmcnt(0)
	v_mfma_f32_16x16x32_bf16 v[32:35], v[216:219], v[32:35], v[40:43]
	ds_read2_b64 v[204:207], v3 offset0:40 offset1:44
	ds_read2_b64 v[208:211], v10 offset0:72 offset1:76
	ds_read2_b64 v[212:215], v60 offset0:104 offset1:108
	ds_read2_b64 v[216:219], v61 offset0:136 offset1:140
	v_mul_f32_e64 v24, v24, v2
	v_mul_f32_e64 v25, v25, v2
	v_pk_mul_f32 v[26:27], v[26:27], v[2:3] op_sel_hi:[1,0]
	v_pk_mul_f32 v[20:21], v[20:21], v[2:3] op_sel_hi:[1,0]
	v_pk_mul_f32 v[22:23], v[22:23], v[2:3] op_sel_hi:[1,0]
	v_bfe_u32 v11, v27, 16, 1
	v_bfe_u32 v40, v26, 16, 1
	v_bfe_u32 v41, v25, 16, 1
	v_bfe_u32 v42, v24, 16, 1
	v_add3_u32 v24, v24, v42, s33
	v_add3_u32 v25, v25, v41, s33
	v_add3_u32 v26, v26, v40, s33
	v_add3_u32 v11, v27, v11, s33
	v_bfe_u32 v27, v20, 16, 1
	v_bfe_u32 v40, v21, 16, 1
	v_bfe_u32 v41, v22, 16, 1
	v_bfe_u32 v42, v23, 16, 1
	v_add3_u32 v42, v23, v42, s33
	v_add3_u32 v41, v22, v41, s33
	v_add3_u32 v40, v21, v40, s33
	v_add3_u32 v27, v20, v27, s33
	v_lshrrev_b32_e32 v43, 16, v27
	v_lshrrev_b32_e32 v40, 16, v40
	v_lshrrev_b32_e32 v41, 16, v41
	v_lshrrev_b32_e32 v27, 16, v42
	v_and_or_b32 v27, v11, s29, v27
	v_and_or_b32 v26, v26, s29, v41
	v_and_or_b32 v25, v25, s29, v40
	v_and_or_b32 v24, v24, s29, v43
	s_waitcnt lgkmcnt(3)
	s_nop 1
	v_mfma_f32_16x16x32_bf16 v[20:23], v[204:207], v[24:27], v[28:31]
	s_waitcnt lgkmcnt(2)
	v_mfma_f32_16x16x32_bf16 v[28:31], v[208:211], v[24:27], v[36:39]
	s_waitcnt lgkmcnt(1)
	v_mfma_f32_16x16x32_bf16 v[36:39], v[212:215], v[24:27], v[44:47]
	s_waitcnt lgkmcnt(0)
	v_mfma_f32_16x16x32_bf16 v[24:27], v[216:219], v[24:27], v[32:35]
	ds_read2_b64 v[204:207], v3 offset0:48 offset1:52
	ds_read2_b64 v[208:211], v10 offset0:80 offset1:84
	ds_read2_b64 v[212:215], v60 offset0:112 offset1:116
	ds_read2_b64 v[216:219], v61 offset0:144 offset1:148
	v_mul_f32_e64 v16, v16, v2
	v_mul_f32_e64 v17, v17, v2
	v_pk_mul_f32 v[18:19], v[18:19], v[2:3] op_sel_hi:[1,0]
	v_pk_mul_f32 v[12:13], v[12:13], v[2:3] op_sel_hi:[1,0]
	v_pk_mul_f32 v[14:15], v[14:15], v[2:3] op_sel_hi:[1,0]
	v_bfe_u32 v11, v19, 16, 1
	v_bfe_u32 v32, v18, 16, 1
	v_bfe_u32 v33, v17, 16, 1
	v_bfe_u32 v34, v16, 16, 1
	v_add3_u32 v16, v16, v34, s33
	v_add3_u32 v17, v17, v33, s33
	v_add3_u32 v18, v18, v32, s33
	v_add3_u32 v11, v19, v11, s33
	v_bfe_u32 v19, v12, 16, 1
	v_bfe_u32 v32, v13, 16, 1
	v_bfe_u32 v33, v14, 16, 1
	v_bfe_u32 v34, v15, 16, 1
	v_add3_u32 v34, v15, v34, s33
	v_add3_u32 v33, v14, v33, s33
	v_add3_u32 v32, v13, v32, s33
	v_add3_u32 v19, v12, v19, s33
	v_lshrrev_b32_e32 v35, 16, v19
	v_lshrrev_b32_e32 v32, 16, v32
	v_lshrrev_b32_e32 v33, 16, v33
	v_lshrrev_b32_e32 v19, 16, v34
	v_and_or_b32 v19, v11, s29, v19
	v_and_or_b32 v18, v18, s29, v33
	v_and_or_b32 v17, v17, s29, v32
	v_and_or_b32 v16, v16, s29, v35
	s_waitcnt lgkmcnt(3)
	s_nop 1
	v_mfma_f32_16x16x32_bf16 v[12:15], v[204:207], v[16:19], v[20:23]
	s_waitcnt lgkmcnt(2)
	v_mfma_f32_16x16x32_bf16 v[20:23], v[208:211], v[16:19], v[28:31]
	s_waitcnt lgkmcnt(1)
	v_mfma_f32_16x16x32_bf16 v[28:31], v[212:215], v[16:19], v[36:39]
	s_waitcnt lgkmcnt(0)
	v_mfma_f32_16x16x32_bf16 v[16:19], v[216:219], v[16:19], v[24:27]
	ds_read2_b64 v[204:207], v3 offset0:56 offset1:60
	ds_read2_b64 v[208:211], v10 offset0:88 offset1:92
	ds_read2_b64 v[212:215], v60 offset0:120 offset1:124
	ds_read2_b64 v[216:219], v61 offset0:152 offset1:156
	v_mul_f32_e64 v8, v8, v2
	v_mul_f32_e64 v9, v9, v2
	v_pk_mul_f32 v[6:7], v[6:7], v[2:3] op_sel_hi:[1,0]
	v_pk_mul_f32 v[4:5], v[4:5], v[2:3] op_sel_hi:[1,0]
	v_pk_mul_f32 v[0:1], v[0:1], v[2:3] op_sel_hi:[1,0]
	v_bfe_u32 v2, v7, 16, 1
	v_bfe_u32 v24, v9, 16, 1
	v_bfe_u32 v25, v8, 16, 1
	v_add3_u32 v8, v8, v25, s33
	v_add3_u32 v9, v9, v24, s33
	v_add3_u32 v7, v7, v2, s33
	v_bfe_u32 v2, v4, 16, 1
	v_bfe_u32 v24, v0, 16, 1
	v_bfe_u32 v25, v1, 16, 1
	v_add3_u32 v25, v1, v25, s33
	v_add3_u32 v24, v0, v24, s33
	v_add3_u32 v4, v4, v2, s33
	v_bfe_u32 v11, v6, 16, 1
	v_add3_u32 v6, v6, v11, s33
	v_bfe_u32 v11, v5, 16, 1
	v_add3_u32 v5, v5, v11, s33
	v_lshrrev_b32_e32 v4, 16, v4
	v_lshrrev_b32_e32 v5, 16, v5
	v_lshrrev_b32_e32 v11, 16, v24
	v_lshrrev_b32_e32 v24, 16, v25
	v_and_or_b32 v27, v7, s29, v24
	v_and_or_b32 v26, v6, s29, v11
	v_and_or_b32 v25, v9, s29, v5
	v_and_or_b32 v24, v8, s29, v4
	s_waitcnt lgkmcnt(3)
	s_nop 1
	v_mfma_f32_16x16x32_bf16 v[12:15], v[204:207], v[24:27], v[12:15]
	s_waitcnt lgkmcnt(2)
	v_mfma_f32_16x16x32_bf16 v[8:11], v[208:211], v[24:27], v[20:23]
	s_waitcnt lgkmcnt(1)
	v_mfma_f32_16x16x32_bf16 v[4:7], v[212:215], v[24:27], v[28:31]
	s_waitcnt lgkmcnt(0)
	v_mfma_f32_16x16x32_bf16 v[0:3], v[216:219], v[24:27], v[16:19]
	s_and_b64 exec, exec, s[0:1]
	s_cbranch_execz .LBB0_91
	s_lshl_b32 s0, s10, 11
	v_bfe_u32 v18, v12, 16, 1
	s_add_u32 s0, s6, s0
	v_add3_u32 v12, v12, v18, s33
	v_bfe_u32 v18, v13, 16, 1
	s_addc_u32 s1, s7, 0
	v_add3_u32 v13, v13, v18, s33
	v_lshrrev_b32_e32 v12, 16, v12
	s_add_u32 s0, s0, s11
	v_and_or_b32 v12, v13, s29, v12
	v_bfe_u32 v13, v14, 16, 1
	s_addc_u32 s1, s1, 0
	v_lshlrev_b64 v[16:17], 11, v[68:69]
	v_add3_u32 v13, v14, v13, s33
	v_bfe_u32 v14, v15, 16, 1
	v_lshl_add_u64 v[16:17], s[0:1], 0, v[16:17]
	v_mov_b32_e32 v71, v80
	v_add3_u32 v14, v15, v14, s33
	v_lshrrev_b32_e32 v13, 16, v13
	v_lshl_add_u64 v[16:17], v[16:17], 0, v[70:71]
	v_and_or_b32 v13, v14, s29, v13
	global_store_dwordx2 v[16:17], v[12:13], off offset:1536
	v_bfe_u32 v12, v8, 16, 1
	v_add3_u32 v8, v8, v12, s33
	v_bfe_u32 v12, v9, 16, 1
	v_add3_u32 v9, v9, v12, s33
	v_lshrrev_b32_e32 v8, 16, v8
	v_and_or_b32 v8, v9, s29, v8
	v_bfe_u32 v9, v10, 16, 1
	v_add3_u32 v9, v10, v9, s33
	v_bfe_u32 v10, v11, 16, 1
	v_add3_u32 v10, v11, v10, s33
	v_lshrrev_b32_e32 v9, 16, v9
	v_and_or_b32 v9, v10, s29, v9
	global_store_dwordx2 v[16:17], v[8:9], off offset:1568
	v_bfe_u32 v8, v4, 16, 1
	v_add3_u32 v4, v4, v8, s33
	v_bfe_u32 v8, v5, 16, 1
	v_add3_u32 v5, v5, v8, s33
	v_lshrrev_b32_e32 v4, 16, v4
	v_and_or_b32 v4, v5, s29, v4
	v_bfe_u32 v5, v6, 16, 1
	v_add3_u32 v5, v6, v5, s33
	v_bfe_u32 v6, v7, 16, 1
	v_add3_u32 v6, v7, v6, s33
	v_lshrrev_b32_e32 v5, 16, v5
	v_and_or_b32 v5, v6, s29, v5
	global_store_dwordx2 v[16:17], v[4:5], off offset:1600
	v_bfe_u32 v4, v0, 16, 1
	v_add3_u32 v0, v0, v4, s33
	v_bfe_u32 v4, v1, 16, 1
	v_add3_u32 v1, v1, v4, s33
	v_lshrrev_b32_e32 v0, 16, v0
	v_and_or_b32 v0, v1, s29, v0
	v_bfe_u32 v1, v2, 16, 1
	v_add3_u32 v1, v2, v1, s33
	v_bfe_u32 v2, v3, 16, 1
	v_add3_u32 v2, v3, v2, s33
	v_lshrrev_b32_e32 v1, 16, v1
	v_and_or_b32 v1, v2, s29, v1
	global_store_dwordx2 v[16:17], v[0:1], off offset:1632

.LBB0_101:
	ds_read_b128 v[12:15], v82
	ds_read_b128 v[16:19], v82 offset:64
	s_waitcnt lgkmcnt(1)
	v_mfma_f32_16x16x32_bf16 v[12:15], v[12:15], v[72:75], 0
	ds_read_b128 v[86:89], v82 offset:32320
	s_waitcnt lgkmcnt(1)
	v_mfma_f32_16x16x32_bf16 v[68:71], v[16:19], v[8:11], v[12:15]
	ds_read_b128 v[16:19], v82 offset:2368
	s_nop 3
	ds_read_b128 v[12:15], v82 offset:2304
	s_waitcnt lgkmcnt(0)
	v_mfma_f32_16x16x32_bf16 v[12:15], v[12:15], v[72:75], 0
	v_mfma_f32_16x16x32_bf16 v[64:67], v[16:19], v[8:11], v[12:15]
	ds_read_b128 v[16:19], v82 offset:4672
	s_nop 5
	ds_read_b128 v[12:15], v82 offset:4608
	s_waitcnt lgkmcnt(0)
	v_mfma_f32_16x16x32_bf16 v[12:15], v[12:15], v[72:75], 0
	v_mfma_f32_16x16x32_bf16 v[60:63], v[16:19], v[8:11], v[12:15]
	ds_read_b128 v[16:19], v82 offset:6976
	s_nop 5
	ds_read_b128 v[12:15], v82 offset:6912
	s_waitcnt lgkmcnt(0)
	v_mfma_f32_16x16x32_bf16 v[12:15], v[12:15], v[72:75], 0
	v_mfma_f32_16x16x32_bf16 v[56:59], v[16:19], v[8:11], v[12:15]
	ds_read_b128 v[16:19], v82 offset:9280
	s_nop 5
	ds_read_b128 v[12:15], v82 offset:9216
	s_waitcnt lgkmcnt(0)
	v_mfma_f32_16x16x32_bf16 v[12:15], v[12:15], v[72:75], 0
	v_mfma_f32_16x16x32_bf16 v[52:55], v[16:19], v[8:11], v[12:15]
	ds_read_b128 v[16:19], v82 offset:11584
	s_nop 5
	ds_read_b128 v[12:15], v82 offset:11520
	s_waitcnt lgkmcnt(0)
	v_mfma_f32_16x16x32_bf16 v[12:15], v[12:15], v[72:75], 0
	v_mfma_f32_16x16x32_bf16 v[48:51], v[16:19], v[8:11], v[12:15]
	ds_read_b128 v[16:19], v82 offset:13888
	s_nop 5
	ds_read_b128 v[12:15], v82 offset:13824
	s_waitcnt lgkmcnt(0)
	v_mfma_f32_16x16x32_bf16 v[12:15], v[12:15], v[72:75], 0
	v_mfma_f32_16x16x32_bf16 v[44:47], v[16:19], v[8:11], v[12:15]
	ds_read_b128 v[16:19], v82 offset:16192
	s_nop 5
	ds_read_b128 v[12:15], v82 offset:16128
	s_waitcnt lgkmcnt(0)
	v_mfma_f32_16x16x32_bf16 v[12:15], v[12:15], v[72:75], 0
	v_mfma_f32_16x16x32_bf16 v[40:43], v[16:19], v[8:11], v[12:15]
	ds_read_b128 v[16:19], v82 offset:18496
	s_nop 5
	ds_read_b128 v[12:15], v82 offset:18432
	s_waitcnt lgkmcnt(0)
	v_mfma_f32_16x16x32_bf16 v[12:15], v[12:15], v[72:75], 0
	v_mfma_f32_16x16x32_bf16 v[36:39], v[16:19], v[8:11], v[12:15]
	ds_read_b128 v[16:19], v82 offset:20800
	s_nop 5
	ds_read_b128 v[12:15], v82 offset:20736
	s_waitcnt lgkmcnt(0)
	v_mfma_f32_16x16x32_bf16 v[12:15], v[12:15], v[72:75], 0
	v_mfma_f32_16x16x32_bf16 v[32:35], v[16:19], v[8:11], v[12:15]
	ds_read_b128 v[16:19], v82 offset:23104
	s_nop 5
	ds_read_b128 v[12:15], v82 offset:23040
	s_waitcnt lgkmcnt(0)
	v_mfma_f32_16x16x32_bf16 v[12:15], v[12:15], v[72:75], 0
	v_mfma_f32_16x16x32_bf16 v[28:31], v[16:19], v[8:11], v[12:15]
	ds_read_b128 v[16:19], v82 offset:25408
	s_nop 5
	ds_read_b128 v[12:15], v82 offset:25344
	s_waitcnt lgkmcnt(0)
	v_mfma_f32_16x16x32_bf16 v[12:15], v[12:15], v[72:75], 0
	v_mfma_f32_16x16x32_bf16 v[24:27], v[16:19], v[8:11], v[12:15]
	ds_read_b128 v[16:19], v82 offset:27712
	s_nop 5
	ds_read_b128 v[12:15], v82 offset:27648
	s_waitcnt lgkmcnt(0)
	v_mfma_f32_16x16x32_bf16 v[12:15], v[12:15], v[72:75], 0
	v_mfma_f32_16x16x32_bf16 v[20:23], v[16:19], v[8:11], v[12:15]
	ds_read_b128 v[16:19], v82 offset:30016
	s_nop 5
	ds_read_b128 v[12:15], v82 offset:29952
	s_waitcnt lgkmcnt(0)
	v_mfma_f32_16x16x32_bf16 v[12:15], v[12:15], v[72:75], 0
	v_mfma_f32_16x16x32_bf16 v[16:19], v[16:19], v[8:11], v[12:15]
	s_nop 6
	ds_read_b128 v[12:15], v82 offset:32256
	s_waitcnt lgkmcnt(0)
	v_mfma_f32_16x16x32_bf16 v[12:15], v[12:15], v[72:75], 0
	v_mfma_f32_16x16x32_bf16 v[12:15], v[86:89], v[8:11], v[12:15]
	ds_read_b128 v[86:89], v82 offset:34560
	s_waitcnt lgkmcnt(0)
	v_mfma_f32_16x16x32_bf16 v[72:75], v[86:89], v[72:75], 0
	ds_read_b128 v[86:89], v82 offset:34624
	s_waitcnt lgkmcnt(0)
	v_mfma_f32_16x16x32_bf16 v[8:11], v[86:89], v[8:11], v[72:75]
	s_nop 4
	v_mul_f32_e32 v72, 0x3e000000, v68
	v_mul_f32_e32 v73, 0x3e000000, v69
	s_mov_b32 s2, 0xff61b1e6
	v_max3_f32 v72, v72, s2, v73
	v_mul_f32_e32 v73, 0x3e000000, v70
	v_mul_f32_e32 v74, 0x3e000000, v71
	v_max3_f32 v72, v72, v73, v74
	v_mul_f32_e32 v73, 0x3e000000, v64
	v_mul_f32_e32 v74, 0x3e000000, v65
	v_max3_f32 v72, v72, v73, v74
	v_mul_f32_e32 v73, 0x3e000000, v66
	v_mul_f32_e32 v74, 0x3e000000, v67
	v_max3_f32 v72, v72, v73, v74
	v_mul_f32_e32 v73, 0x3e000000, v60
	v_mul_f32_e32 v74, 0x3e000000, v61
	v_max3_f32 v72, v72, v73, v74
	v_mul_f32_e32 v73, 0x3e000000, v62
	v_mul_f32_e32 v74, 0x3e000000, v63
	v_max3_f32 v72, v72, v73, v74
	v_mul_f32_e32 v73, 0x3e000000, v56
	v_mul_f32_e32 v74, 0x3e000000, v57
	v_max3_f32 v72, v72, v73, v74
	v_mul_f32_e32 v73, 0x3e000000, v58
	v_mul_f32_e32 v74, 0x3e000000, v59
	v_max3_f32 v72, v72, v73, v74
	v_mul_f32_e32 v73, 0x3e000000, v52
	v_mul_f32_e32 v74, 0x3e000000, v53
	v_max3_f32 v72, v72, v73, v74
	v_mul_f32_e32 v73, 0x3e000000, v54
	v_mul_f32_e32 v74, 0x3e000000, v55
	v_max3_f32 v72, v72, v73, v74
	v_mul_f32_e32 v73, 0x3e000000, v48
	v_mul_f32_e32 v74, 0x3e000000, v49
	v_max3_f32 v72, v72, v73, v74
	v_mul_f32_e32 v73, 0x3e000000, v50
	v_mul_f32_e32 v74, 0x3e000000, v51
	v_max3_f32 v72, v72, v73, v74
	v_mul_f32_e32 v73, 0x3e000000, v44
	v_mul_f32_e32 v74, 0x3e000000, v45
	v_max3_f32 v72, v72, v73, v74
	v_mul_f32_e32 v73, 0x3e000000, v46
	v_mul_f32_e32 v74, 0x3e000000, v47
	v_max3_f32 v72, v72, v73, v74
	v_mul_f32_e32 v73, 0x3e000000, v40
	v_mul_f32_e32 v74, 0x3e000000, v41
	v_max3_f32 v72, v72, v73, v74
	v_mul_f32_e32 v73, 0x3e000000, v42
	v_mul_f32_e32 v74, 0x3e000000, v43
	v_max3_f32 v72, v72, v73, v74
	v_mul_f32_e32 v73, 0x3e000000, v36
	v_mul_f32_e32 v74, 0x3e000000, v37
	v_max3_f32 v72, v72, v73, v74
	v_mul_f32_e32 v73, 0x3e000000, v38
	v_mul_f32_e32 v74, 0x3e000000, v39
	v_max3_f32 v72, v72, v73, v74
	v_mul_f32_e32 v73, 0x3e000000, v32
	v_mul_f32_e32 v74, 0x3e000000, v33
	v_max3_f32 v72, v72, v73, v74
	v_mul_f32_e32 v73, 0x3e000000, v34
	v_mul_f32_e32 v74, 0x3e000000, v35
	v_max3_f32 v72, v72, v73, v74
	v_mul_f32_e32 v73, 0x3e000000, v28
	v_mul_f32_e32 v74, 0x3e000000, v29
	v_max3_f32 v72, v72, v73, v74
	v_mul_f32_e32 v73, 0x3e000000, v30
	v_mul_f32_e32 v74, 0x3e000000, v31
	v_max3_f32 v72, v72, v73, v74
	v_mul_f32_e32 v73, 0x3e000000, v24
	v_mul_f32_e32 v74, 0x3e000000, v25
	v_max3_f32 v72, v72, v73, v74
	v_mul_f32_e32 v73, 0x3e000000, v26
	v_mul_f32_e32 v74, 0x3e000000, v27
	v_max3_f32 v72, v72, v73, v74
	v_mul_f32_e32 v73, 0x3e000000, v20
	v_mul_f32_e32 v74, 0x3e000000, v21
	v_max3_f32 v72, v72, v73, v74
	v_mul_f32_e32 v73, 0x3e000000, v22
	v_mul_f32_e32 v74, 0x3e000000, v23
	v_max3_f32 v72, v72, v73, v74
	v_mul_f32_e32 v73, 0x3e000000, v16
	v_mul_f32_e32 v74, 0x3e000000, v17
	v_max3_f32 v72, v72, v73, v74
	v_mul_f32_e32 v73, 0x3e000000, v18
	v_mul_f32_e32 v74, 0x3e000000, v19
	v_max3_f32 v72, v72, v73, v74
	v_mul_f32_e32 v73, 0x3e000000, v12
	v_mul_f32_e32 v74, 0x3e000000, v13
	v_max3_f32 v72, v72, v73, v74
	v_mul_f32_e32 v73, 0x3e000000, v14
	v_mul_f32_e32 v74, 0x3e000000, v15
	v_max3_f32 v72, v72, v73, v74
	v_mul_f32_e32 v73, 0x3e000000, v8
	v_mul_f32_e32 v74, 0x3e000000, v9
	v_max3_f32 v72, v72, v73, v74
	v_mul_f32_e32 v73, 0x3e000000, v10
	v_mul_f32_e32 v74, 0x3e000000, v11
	v_max3_f32 v72, v72, v73, v74
	ds_bpermute_b32 v73, v83, v72
	s_mov_b32 s2, 0x3e000000
	s_waitcnt lgkmcnt(0)
	v_max_f32_e32 v73, v73, v73
	v_max_f32_e32 v72, v72, v73
	ds_bpermute_b32 v73, v84, v72
	s_waitcnt lgkmcnt(0)
	v_max_f32_e32 v73, v73, v73
	v_max_f32_e32 v86, v72, v73
	v_fma_f32 v68, v68, s2, -v86
	v_fma_f32 v69, v69, s2, -v86
	v_mul_f32_e32 v68, 0x3fb8aa3b, v68
	v_mul_f32_e32 v69, 0x3fb8aa3b, v69
	v_exp_f32_e32 v68, v68
	v_exp_f32_e32 v72, v69
	v_fma_f32 v69, v70, s2, -v86
	v_mul_f32_e32 v69, 0x3fb8aa3b, v69
	v_fma_f32 v70, v71, s2, -v86
	v_exp_f32_e32 v69, v69
	v_mul_f32_e32 v70, 0x3fb8aa3b, v70
	v_exp_f32_e32 v73, v70
	v_add_f32_e32 v70, 0, v68
	v_add_f32_e32 v70, v72, v70
	v_fma_f32 v64, v64, s2, -v86
	v_add_f32_e32 v70, v69, v70
	v_mul_f32_e32 v64, 0x3fb8aa3b, v64
	v_add_f32_e32 v87, v73, v70
	v_exp_f32_e32 v70, v64
	v_fma_f32 v64, v65, s2, -v86
	v_mul_f32_e32 v64, 0x3fb8aa3b, v64
	v_exp_f32_e32 v74, v64
	v_fma_f32 v64, v66, s2, -v86
	v_mul_f32_e32 v64, 0x3fb8aa3b, v64
	v_exp_f32_e32 v71, v64
	v_fma_f32 v64, v67, s2, -v86
	v_mul_f32_e32 v64, 0x3fb8aa3b, v64
	v_exp_f32_e32 v75, v64
	v_add_f32_e32 v64, v70, v87
	v_add_f32_e32 v64, v74, v64
	v_fma_f32 v60, v60, s2, -v86
	v_fma_f32 v61, v61, s2, -v86
	v_add_f32_e32 v64, v71, v64
	v_mul_f32_e32 v60, 0x3fb8aa3b, v60
	v_mul_f32_e32 v61, 0x3fb8aa3b, v61
	v_add_f32_e32 v66, v75, v64
	v_exp_f32_e32 v60, v60
	v_exp_f32_e32 v64, v61
	v_fma_f32 v61, v62, s2, -v86
	v_mul_f32_e32 v61, 0x3fb8aa3b, v61
	v_fma_f32 v62, v63, s2, -v86
	v_exp_f32_e32 v61, v61
	v_mul_f32_e32 v62, 0x3fb8aa3b, v62
	v_exp_f32_e32 v65, v62
	v_add_f32_e32 v62, v60, v66
	v_add_f32_e32 v62, v64, v62
	v_fma_f32 v56, v56, s2, -v86
	v_add_f32_e32 v62, v61, v62
	v_mul_f32_e32 v56, 0x3fb8aa3b, v56
	v_add_f32_e32 v87, v65, v62
	v_exp_f32_e32 v62, v56
	v_fma_f32 v56, v57, s2, -v86
	v_mul_f32_e32 v56, 0x3fb8aa3b, v56
	v_exp_f32_e32 v66, v56
	v_fma_f32 v56, v58, s2, -v86
	v_mul_f32_e32 v56, 0x3fb8aa3b, v56
	v_exp_f32_e32 v63, v56
	v_fma_f32 v56, v59, s2, -v86
	v_mul_f32_e32 v56, 0x3fb8aa3b, v56
	v_exp_f32_e32 v67, v56
	v_add_f32_e32 v56, v62, v87
	v_add_f32_e32 v56, v66, v56
	v_fma_f32 v52, v52, s2, -v86
	v_fma_f32 v53, v53, s2, -v86
	v_add_f32_e32 v56, v63, v56
	v_mul_f32_e32 v52, 0x3fb8aa3b, v52
	v_mul_f32_e32 v53, 0x3fb8aa3b, v53
	v_add_f32_e32 v58, v67, v56
	v_exp_f32_e32 v52, v52
	v_exp_f32_e32 v56, v53
	v_fma_f32 v53, v54, s2, -v86
	v_mul_f32_e32 v53, 0x3fb8aa3b, v53
	v_fma_f32 v54, v55, s2, -v86
	v_exp_f32_e32 v53, v53
	v_mul_f32_e32 v54, 0x3fb8aa3b, v54
	v_exp_f32_e32 v57, v54
	v_add_f32_e32 v54, v52, v58
	v_add_f32_e32 v54, v56, v54
	v_fma_f32 v48, v48, s2, -v86
	v_add_f32_e32 v54, v53, v54
	v_mul_f32_e32 v48, 0x3fb8aa3b, v48
	v_add_f32_e32 v87, v57, v54
	v_exp_f32_e32 v54, v48
	v_fma_f32 v48, v49, s2, -v86
	v_mul_f32_e32 v48, 0x3fb8aa3b, v48
	v_exp_f32_e32 v58, v48
	v_fma_f32 v48, v50, s2, -v86
	v_mul_f32_e32 v48, 0x3fb8aa3b, v48
	v_exp_f32_e32 v55, v48
	v_fma_f32 v48, v51, s2, -v86
	v_mul_f32_e32 v48, 0x3fb8aa3b, v48
	v_exp_f32_e32 v59, v48
	v_add_f32_e32 v48, v54, v87
	v_add_f32_e32 v48, v58, v48
	v_fma_f32 v44, v44, s2, -v86
	v_fma_f32 v45, v45, s2, -v86
	v_add_f32_e32 v48, v55, v48
	v_mul_f32_e32 v44, 0x3fb8aa3b, v44
	v_mul_f32_e32 v45, 0x3fb8aa3b, v45
	v_add_f32_e32 v50, v59, v48
	v_exp_f32_e32 v44, v44
	v_exp_f32_e32 v48, v45
	v_fma_f32 v45, v46, s2, -v86
	v_mul_f32_e32 v45, 0x3fb8aa3b, v45
	v_fma_f32 v46, v47, s2, -v86
	v_exp_f32_e32 v45, v45
	v_mul_f32_e32 v46, 0x3fb8aa3b, v46
	v_exp_f32_e32 v49, v46
	v_add_f32_e32 v46, v44, v50
	v_add_f32_e32 v46, v48, v46
	v_fma_f32 v40, v40, s2, -v86
	v_add_f32_e32 v46, v45, v46
	v_mul_f32_e32 v40, 0x3fb8aa3b, v40
	v_add_f32_e32 v87, v49, v46
	v_exp_f32_e32 v46, v40
	v_fma_f32 v40, v41, s2, -v86
	v_mul_f32_e32 v40, 0x3fb8aa3b, v40
	v_exp_f32_e32 v50, v40
	v_fma_f32 v40, v42, s2, -v86
	v_mul_f32_e32 v40, 0x3fb8aa3b, v40
	v_exp_f32_e32 v47, v40
	v_fma_f32 v40, v43, s2, -v86
	v_mul_f32_e32 v40, 0x3fb8aa3b, v40
	v_exp_f32_e32 v51, v40
	v_add_f32_e32 v40, v46, v87
	v_add_f32_e32 v40, v50, v40
	v_fma_f32 v36, v36, s2, -v86
	v_fma_f32 v37, v37, s2, -v86
	v_add_f32_e32 v40, v47, v40
	v_mul_f32_e32 v36, 0x3fb8aa3b, v36
	v_mul_f32_e32 v37, 0x3fb8aa3b, v37
	v_add_f32_e32 v42, v51, v40
	v_exp_f32_e32 v36, v36
	v_exp_f32_e32 v40, v37
	v_fma_f32 v37, v38, s2, -v86
	v_mul_f32_e32 v37, 0x3fb8aa3b, v37
	v_fma_f32 v38, v39, s2, -v86
	v_exp_f32_e32 v37, v37
	v_mul_f32_e32 v38, 0x3fb8aa3b, v38
	v_exp_f32_e32 v41, v38
	v_add_f32_e32 v38, v36, v42
	v_add_f32_e32 v38, v40, v38
	v_fma_f32 v32, v32, s2, -v86
	v_add_f32_e32 v38, v37, v38
	v_mul_f32_e32 v32, 0x3fb8aa3b, v32
	v_add_f32_e32 v87, v41, v38
	v_exp_f32_e32 v38, v32
	v_fma_f32 v32, v33, s2, -v86
	v_mul_f32_e32 v32, 0x3fb8aa3b, v32
	v_exp_f32_e32 v42, v32
	v_fma_f32 v32, v34, s2, -v86
	v_mul_f32_e32 v32, 0x3fb8aa3b, v32
	v_exp_f32_e32 v39, v32
	v_fma_f32 v32, v35, s2, -v86
	v_mul_f32_e32 v32, 0x3fb8aa3b, v32
	v_exp_f32_e32 v43, v32
	v_add_f32_e32 v32, v38, v87
	v_add_f32_e32 v32, v42, v32
	v_fma_f32 v28, v28, s2, -v86
	v_fma_f32 v29, v29, s2, -v86
	v_add_f32_e32 v32, v39, v32
	v_mul_f32_e32 v28, 0x3fb8aa3b, v28
	v_mul_f32_e32 v29, 0x3fb8aa3b, v29
	v_add_f32_e32 v34, v43, v32
	v_exp_f32_e32 v28, v28
	v_exp_f32_e32 v32, v29
	v_fma_f32 v29, v30, s2, -v86
	v_mul_f32_e32 v29, 0x3fb8aa3b, v29
	v_fma_f32 v30, v31, s2, -v86
	v_exp_f32_e32 v29, v29
	v_mul_f32_e32 v30, 0x3fb8aa3b, v30
	v_exp_f32_e32 v33, v30
	v_add_f32_e32 v30, v28, v34
	v_add_f32_e32 v30, v32, v30
	v_fma_f32 v24, v24, s2, -v86
	v_add_f32_e32 v30, v29, v30
	v_mul_f32_e32 v24, 0x3fb8aa3b, v24
	v_add_f32_e32 v87, v33, v30
	v_exp_f32_e32 v30, v24
	v_fma_f32 v24, v25, s2, -v86
	v_mul_f32_e32 v24, 0x3fb8aa3b, v24
	v_exp_f32_e32 v34, v24
	v_fma_f32 v24, v26, s2, -v86
	v_mul_f32_e32 v24, 0x3fb8aa3b, v24
	v_exp_f32_e32 v31, v24
	v_fma_f32 v24, v27, s2, -v86
	v_mul_f32_e32 v24, 0x3fb8aa3b, v24
	v_exp_f32_e32 v35, v24
	v_add_f32_e32 v24, v30, v87
	v_add_f32_e32 v24, v34, v24
	v_fma_f32 v20, v20, s2, -v86
	v_fma_f32 v21, v21, s2, -v86
	v_add_f32_e32 v24, v31, v24
	v_mul_f32_e32 v20, 0x3fb8aa3b, v20
	v_mul_f32_e32 v21, 0x3fb8aa3b, v21
	v_add_f32_e32 v26, v35, v24
	v_exp_f32_e32 v20, v20
	v_exp_f32_e32 v24, v21
	v_fma_f32 v21, v22, s2, -v86
	v_mul_f32_e32 v21, 0x3fb8aa3b, v21
	v_fma_f32 v22, v23, s2, -v86
	v_exp_f32_e32 v21, v21
	v_mul_f32_e32 v22, 0x3fb8aa3b, v22
	v_exp_f32_e32 v25, v22
	v_add_f32_e32 v22, v20, v26
	v_add_f32_e32 v22, v24, v22
	v_fma_f32 v16, v16, s2, -v86
	v_add_f32_e32 v22, v21, v22
	v_mul_f32_e32 v16, 0x3fb8aa3b, v16
	v_add_f32_e32 v87, v25, v22
	v_exp_f32_e32 v22, v16
	v_fma_f32 v16, v17, s2, -v86
	v_mul_f32_e32 v16, 0x3fb8aa3b, v16
	v_exp_f32_e32 v26, v16
	v_fma_f32 v16, v18, s2, -v86
	v_mul_f32_e32 v16, 0x3fb8aa3b, v16
	v_exp_f32_e32 v23, v16
	v_fma_f32 v16, v19, s2, -v86
	v_mul_f32_e32 v16, 0x3fb8aa3b, v16
	v_exp_f32_e32 v27, v16
	v_add_f32_e32 v16, v22, v87
	v_add_f32_e32 v16, v26, v16
	v_fma_f32 v12, v12, s2, -v86
	v_fma_f32 v13, v13, s2, -v86
	v_add_f32_e32 v16, v23, v16
	v_mul_f32_e32 v12, 0x3fb8aa3b, v12
	v_mul_f32_e32 v13, 0x3fb8aa3b, v13
	v_add_f32_e32 v18, v27, v16
	v_exp_f32_e32 v12, v12
	v_exp_f32_e32 v16, v13
	v_fma_f32 v13, v14, s2, -v86
	v_mul_f32_e32 v13, 0x3fb8aa3b, v13
	v_fma_f32 v14, v15, s2, -v86
	v_exp_f32_e32 v13, v13
	v_mul_f32_e32 v14, 0x3fb8aa3b, v14
	v_exp_f32_e32 v17, v14
	v_add_f32_e32 v14, v12, v18
	v_add_f32_e32 v14, v16, v14
	v_fma_f32 v8, v8, s2, -v86
	v_fma_f32 v9, v9, s2, -v86
	v_add_f32_e32 v14, v13, v14
	v_mul_f32_e32 v8, 0x3fb8aa3b, v8
	v_mul_f32_e32 v9, 0x3fb8aa3b, v9
	v_add_f32_e32 v18, v17, v14
	v_exp_f32_e32 v8, v8
	v_exp_f32_e32 v14, v9
	v_fma_f32 v9, v10, s2, -v86
	v_mul_f32_e32 v9, 0x3fb8aa3b, v9
	v_fma_f32 v10, v11, s2, -v86
	v_exp_f32_e32 v9, v9
	v_mul_f32_e32 v10, 0x3fb8aa3b, v10
	v_exp_f32_e32 v15, v10
	v_add_f32_e32 v10, v8, v18
	v_add_f32_e32 v10, v14, v10
	v_add_f32_e32 v10, v9, v10
	v_add_f32_e32 v10, v15, v10
	ds_bpermute_b32 v11, v83, v10
	s_waitcnt lgkmcnt(0)
	v_add_f32_e32 v10, v10, v11
	ds_bpermute_b32 v11, v84, v10
	s_waitcnt lgkmcnt(0)
	v_add_f32_e32 v10, v10, v11
	v_div_scale_f32 v11, s[2:3], v10, v10, 1.0
	v_rcp_f32_e32 v18, v11
	v_div_scale_f32 v19, vcc, 1.0, v10, 1.0
	v_fma_f32 v86, -v11, v18, 1.0
	v_fmac_f32_e32 v18, v86, v18
	v_mul_f32_e32 v86, v19, v18
	v_fma_f32 v87, -v11, v86, v19
	v_fmac_f32_e32 v86, v87, v18
	v_fma_f32 v11, -v11, v86, v19
	v_div_fmas_f32 v11, v11, v18, v86
	v_div_fixup_f32 v10, v11, v10, 1.0
	v_pk_mul_f32 v[18:19], v[68:69], v[10:11] op_sel_hi:[1,0]
	v_pk_mul_f32 v[68:69], v[72:73], v[10:11] op_sel_hi:[1,0]
	v_pk_mul_f32 v[72:73], v[74:75], v[10:11] op_sel_hi:[1,0]
	v_pk_mul_f32 v[70:71], v[70:71], v[10:11] op_sel_hi:[1,0]
	v_bfe_u32 v11, v73, 16, 1
	v_bfe_u32 v74, v72, 16, 1
	v_bfe_u32 v75, v69, 16, 1
	v_bfe_u32 v86, v68, 16, 1
	v_add3_u32 v73, v73, v11, s33
	v_bfe_u32 v11, v18, 16, 1
	v_add3_u32 v86, v68, v86, s33
	v_add3_u32 v87, v69, v75, s33
	v_add3_u32 v72, v72, v74, s33
	v_bfe_u32 v68, v19, 16, 1
	v_bfe_u32 v69, v70, 16, 1
	v_bfe_u32 v74, v71, 16, 1
	v_add3_u32 v18, v18, v11, s33
	v_add_u32_e32 v11, 0x9000, v85
	v_add3_u32 v74, v71, v74, s33
	v_add3_u32 v75, v70, v69, s33
	v_add3_u32 v19, v19, v68, s33
	ds_read2_b64 v[68:71], v11 offset1:4
	v_lshrrev_b32_e32 v18, 16, v18
	v_lshrrev_b32_e32 v19, 16, v19
	v_lshrrev_b32_e32 v88, 16, v75
	v_lshrrev_b32_e32 v74, 16, v74
	v_and_or_b32 v75, v73, s29, v74
	v_and_or_b32 v74, v72, s29, v88
	v_and_or_b32 v73, v87, s29, v19
	v_and_or_b32 v72, v86, s29, v18
	v_add_u32_e32 v18, 0xb000, v85
	s_waitcnt lgkmcnt(0)
	v_mfma_f32_16x16x32_bf16 v[86:89], v[68:71], v[72:75], 0
	ds_read2_b64 v[68:71], v18 offset0:32 offset1:36
	s_waitcnt lgkmcnt(0)
	v_mfma_f32_16x16x32_bf16 v[90:93], v[68:71], v[72:75], 0
	v_add_u32_e32 v68, 0xd000, v85
	v_add_u32_e32 v69, 0xf000, v85
	ds_read2_b64 v[94:97], v68 offset0:64 offset1:68
	ds_read2_b64 v[98:101], v69 offset0:96 offset1:100
	s_waitcnt lgkmcnt(1)
	v_mfma_f32_16x16x32_bf16 v[94:97], v[94:97], v[72:75], 0
	s_waitcnt lgkmcnt(0)
	v_mfma_f32_16x16x32_bf16 v[70:73], v[98:101], v[72:75], 0
	ds_read2_b64 v[204:207], v11 offset0:8 offset1:12
	ds_read2_b64 v[208:211], v18 offset0:40 offset1:44
	ds_read2_b64 v[212:215], v68 offset0:72 offset1:76
	ds_read2_b64 v[216:219], v69 offset0:104 offset1:108
	v_mul_f32_e64 v64, v64, v10
	v_mul_f32_e64 v65, v65, v10
	v_pk_mul_f32 v[66:67], v[66:67], v[10:11] op_sel_hi:[1,0]
	v_pk_mul_f32 v[60:61], v[60:61], v[10:11] op_sel_hi:[1,0]
	v_pk_mul_f32 v[62:63], v[62:63], v[10:11] op_sel_hi:[1,0]
	v_bfe_u32 v19, v67, 16, 1
	v_bfe_u32 v74, v66, 16, 1
	v_bfe_u32 v75, v65, 16, 1
	v_bfe_u32 v98, v64, 16, 1
	v_add3_u32 v64, v64, v98, s33
	v_add3_u32 v65, v65, v75, s33
	v_add3_u32 v66, v66, v74, s33
	v_add3_u32 v19, v67, v19, s33
	v_bfe_u32 v67, v60, 16, 1
	v_bfe_u32 v74, v61, 16, 1
	v_bfe_u32 v75, v62, 16, 1
	v_bfe_u32 v98, v63, 16, 1
	v_add3_u32 v98, v63, v98, s33
	v_add3_u32 v75, v62, v75, s33
	v_add3_u32 v74, v61, v74, s33
	v_add3_u32 v67, v60, v67, s33
	v_lshrrev_b32_e32 v99, 16, v67
	v_lshrrev_b32_e32 v74, 16, v74
	v_lshrrev_b32_e32 v75, 16, v75
	v_lshrrev_b32_e32 v67, 16, v98
	v_and_or_b32 v67, v19, s29, v67
	v_and_or_b32 v66, v66, s29, v75
	v_and_or_b32 v65, v65, s29, v74
	v_and_or_b32 v64, v64, s29, v99
	s_waitcnt lgkmcnt(3)
	s_nop 1
	v_mfma_f32_16x16x32_bf16 v[60:63], v[204:207], v[64:67], v[86:89]
	s_waitcnt lgkmcnt(2)
	v_mfma_f32_16x16x32_bf16 v[86:89], v[208:211], v[64:67], v[90:93]
	s_waitcnt lgkmcnt(1)
	v_mfma_f32_16x16x32_bf16 v[90:93], v[212:215], v[64:67], v[94:97]
	s_waitcnt lgkmcnt(0)
	v_mfma_f32_16x16x32_bf16 v[64:67], v[216:219], v[64:67], v[70:73]
	ds_read2_b64 v[204:207], v11 offset0:16 offset1:20
	ds_read2_b64 v[208:211], v18 offset0:48 offset1:52
	ds_read2_b64 v[212:215], v68 offset0:80 offset1:84
	ds_read2_b64 v[216:219], v69 offset0:112 offset1:116
	v_mul_f32_e64 v56, v56, v10
	v_mul_f32_e64 v57, v57, v10
	v_pk_mul_f32 v[58:59], v[58:59], v[10:11] op_sel_hi:[1,0]
	v_pk_mul_f32 v[52:53], v[52:53], v[10:11] op_sel_hi:[1,0]
	v_pk_mul_f32 v[54:55], v[54:55], v[10:11] op_sel_hi:[1,0]
	v_bfe_u32 v19, v59, 16, 1
	v_bfe_u32 v70, v58, 16, 1
	v_bfe_u32 v71, v57, 16, 1
	v_bfe_u32 v72, v56, 16, 1
	v_add3_u32 v56, v56, v72, s33
	v_add3_u32 v57, v57, v71, s33
	v_add3_u32 v58, v58, v70, s33
	v_add3_u32 v19, v59, v19, s33
	v_bfe_u32 v59, v52, 16, 1
	v_bfe_u32 v70, v53, 16, 1
	v_bfe_u32 v71, v54, 16, 1
	v_bfe_u32 v72, v55, 16, 1
	v_add3_u32 v72, v55, v72, s33
	v_add3_u32 v71, v54, v71, s33
	v_add3_u32 v70, v53, v70, s33
	v_add3_u32 v59, v52, v59, s33
	v_lshrrev_b32_e32 v73, 16, v59
	v_lshrrev_b32_e32 v70, 16, v70
	v_lshrrev_b32_e32 v71, 16, v71
	v_lshrrev_b32_e32 v59, 16, v72
	v_and_or_b32 v59, v19, s29, v59
	v_and_or_b32 v58, v58, s29, v71
	v_and_or_b32 v57, v57, s29, v70
	v_and_or_b32 v56, v56, s29, v73
	s_waitcnt lgkmcnt(3)
	s_nop 1
	v_mfma_f32_16x16x32_bf16 v[52:55], v[204:207], v[56:59], v[60:63]
	s_waitcnt lgkmcnt(2)
	v_mfma_f32_16x16x32_bf16 v[60:63], v[208:211], v[56:59], v[86:89]
	s_waitcnt lgkmcnt(1)
	v_mfma_f32_16x16x32_bf16 v[70:73], v[212:215], v[56:59], v[90:93]
	s_waitcnt lgkmcnt(0)
	v_mfma_f32_16x16x32_bf16 v[56:59], v[216:219], v[56:59], v[64:67]
	ds_read2_b64 v[204:207], v11 offset0:24 offset1:28
	ds_read2_b64 v[208:211], v18 offset0:56 offset1:60
	ds_read2_b64 v[212:215], v68 offset0:88 offset1:92
	ds_read2_b64 v[216:219], v69 offset0:120 offset1:124
	v_mul_f32_e64 v48, v48, v10
	v_mul_f32_e64 v49, v49, v10
	v_pk_mul_f32 v[50:51], v[50:51], v[10:11] op_sel_hi:[1,0]
	v_pk_mul_f32 v[44:45], v[44:45], v[10:11] op_sel_hi:[1,0]
	v_pk_mul_f32 v[46:47], v[46:47], v[10:11] op_sel_hi:[1,0]
	v_bfe_u32 v19, v51, 16, 1
	v_bfe_u32 v64, v50, 16, 1
	v_bfe_u32 v65, v49, 16, 1
	v_bfe_u32 v66, v48, 16, 1
	v_add3_u32 v48, v48, v66, s33
	v_add3_u32 v49, v49, v65, s33
	v_add3_u32 v50, v50, v64, s33
	v_add3_u32 v19, v51, v19, s33
	v_bfe_u32 v51, v44, 16, 1
	v_bfe_u32 v64, v45, 16, 1
	v_bfe_u32 v65, v46, 16, 1
	v_bfe_u32 v66, v47, 16, 1
	v_add3_u32 v66, v47, v66, s33
	v_add3_u32 v65, v46, v65, s33
	v_add3_u32 v64, v45, v64, s33
	v_add3_u32 v51, v44, v51, s33
	v_lshrrev_b32_e32 v67, 16, v51
	v_lshrrev_b32_e32 v64, 16, v64
	v_lshrrev_b32_e32 v65, 16, v65
	v_lshrrev_b32_e32 v51, 16, v66
	v_and_or_b32 v51, v19, s29, v51
	v_and_or_b32 v50, v50, s29, v65
	v_and_or_b32 v49, v49, s29, v64
	v_and_or_b32 v48, v48, s29, v67
	s_waitcnt lgkmcnt(3)
	s_nop 1
	v_mfma_f32_16x16x32_bf16 v[44:47], v[204:207], v[48:51], v[52:55]
	s_waitcnt lgkmcnt(2)
	v_mfma_f32_16x16x32_bf16 v[52:55], v[208:211], v[48:51], v[60:63]
	s_waitcnt lgkmcnt(1)
	v_mfma_f32_16x16x32_bf16 v[60:63], v[212:215], v[48:51], v[70:73]
	s_waitcnt lgkmcnt(0)
	v_mfma_f32_16x16x32_bf16 v[48:51], v[216:219], v[48:51], v[56:59]
	ds_read2_b64 v[204:207], v11 offset0:32 offset1:36
	ds_read2_b64 v[208:211], v18 offset0:64 offset1:68
	ds_read2_b64 v[212:215], v68 offset0:96 offset1:100
	ds_read2_b64 v[216:219], v69 offset0:128 offset1:132
	v_mul_f32_e64 v40, v40, v10
	v_mul_f32_e64 v41, v41, v10
	v_pk_mul_f32 v[42:43], v[42:43], v[10:11] op_sel_hi:[1,0]
	v_pk_mul_f32 v[36:37], v[36:37], v[10:11] op_sel_hi:[1,0]
	v_pk_mul_f32 v[38:39], v[38:39], v[10:11] op_sel_hi:[1,0]
	v_bfe_u32 v19, v43, 16, 1
	v_bfe_u32 v56, v42, 16, 1
	v_bfe_u32 v57, v41, 16, 1
	v_bfe_u32 v58, v40, 16, 1
	v_add3_u32 v40, v40, v58, s33
	v_add3_u32 v41, v41, v57, s33
	v_add3_u32 v42, v42, v56, s33
	v_add3_u32 v19, v43, v19, s33
	v_bfe_u32 v43, v36, 16, 1
	v_bfe_u32 v56, v37, 16, 1
	v_bfe_u32 v57, v38, 16, 1
	v_bfe_u32 v58, v39, 16, 1
	v_add3_u32 v58, v39, v58, s33
	v_add3_u32 v57, v38, v57, s33
	v_add3_u32 v56, v37, v56, s33
	v_add3_u32 v43, v36, v43, s33
	v_lshrrev_b32_e32 v59, 16, v43
	v_lshrrev_b32_e32 v56, 16, v56
	v_lshrrev_b32_e32 v57, 16, v57
	v_lshrrev_b32_e32 v43, 16, v58
	v_and_or_b32 v43, v19, s29, v43
	v_and_or_b32 v42, v42, s29, v57
	v_and_or_b32 v41, v41, s29, v56
	v_and_or_b32 v40, v40, s29, v59
	s_waitcnt lgkmcnt(3)
	s_nop 1
	v_mfma_f32_16x16x32_bf16 v[36:39], v[204:207], v[40:43], v[44:47]
	s_waitcnt lgkmcnt(2)
	v_mfma_f32_16x16x32_bf16 v[44:47], v[208:211], v[40:43], v[52:55]
	s_waitcnt lgkmcnt(1)
	v_mfma_f32_16x16x32_bf16 v[52:55], v[212:215], v[40:43], v[60:63]
	s_waitcnt lgkmcnt(0)
	v_mfma_f32_16x16x32_bf16 v[40:43], v[216:219], v[40:43], v[48:51]
	ds_read2_b64 v[204:207], v11 offset0:40 offset1:44
	ds_read2_b64 v[208:211], v18 offset0:72 offset1:76
	ds_read2_b64 v[212:215], v68 offset0:104 offset1:108
	ds_read2_b64 v[216:219], v69 offset0:136 offset1:140
	v_mul_f32_e64 v32, v32, v10
	v_mul_f32_e64 v33, v33, v10
	v_pk_mul_f32 v[34:35], v[34:35], v[10:11] op_sel_hi:[1,0]
	v_pk_mul_f32 v[28:29], v[28:29], v[10:11] op_sel_hi:[1,0]
	v_pk_mul_f32 v[30:31], v[30:31], v[10:11] op_sel_hi:[1,0]
	v_bfe_u32 v19, v35, 16, 1
	v_bfe_u32 v48, v34, 16, 1
	v_bfe_u32 v49, v33, 16, 1
	v_bfe_u32 v50, v32, 16, 1
	v_add3_u32 v32, v32, v50, s33
	v_add3_u32 v33, v33, v49, s33
	v_add3_u32 v34, v34, v48, s33
	v_add3_u32 v19, v35, v19, s33
	v_bfe_u32 v35, v28, 16, 1
	v_bfe_u32 v48, v29, 16, 1
	v_bfe_u32 v49, v30, 16, 1
	v_bfe_u32 v50, v31, 16, 1
	v_add3_u32 v50, v31, v50, s33
	v_add3_u32 v49, v30, v49, s33
	v_add3_u32 v48, v29, v48, s33
	v_add3_u32 v35, v28, v35, s33
	v_lshrrev_b32_e32 v51, 16, v35
	v_lshrrev_b32_e32 v48, 16, v48
	v_lshrrev_b32_e32 v49, 16, v49
	v_lshrrev_b32_e32 v35, 16, v50
	v_and_or_b32 v35, v19, s29, v35
	v_and_or_b32 v34, v34, s29, v49
	v_and_or_b32 v33, v33, s29, v48
	v_and_or_b32 v32, v32, s29, v51
	s_waitcnt lgkmcnt(3)
	s_nop 1
	v_mfma_f32_16x16x32_bf16 v[28:31], v[204:207], v[32:35], v[36:39]
	s_waitcnt lgkmcnt(2)
	v_mfma_f32_16x16x32_bf16 v[36:39], v[208:211], v[32:35], v[44:47]
	s_waitcnt lgkmcnt(1)
	v_mfma_f32_16x16x32_bf16 v[44:47], v[212:215], v[32:35], v[52:55]
	s_waitcnt lgkmcnt(0)
	v_mfma_f32_16x16x32_bf16 v[32:35], v[216:219], v[32:35], v[40:43]
	ds_read2_b64 v[204:207], v11 offset0:48 offset1:52
	ds_read2_b64 v[208:211], v18 offset0:80 offset1:84
	ds_read2_b64 v[212:215], v68 offset0:112 offset1:116
	ds_read2_b64 v[216:219], v69 offset0:144 offset1:148
	v_mul_f32_e64 v24, v24, v10
	v_mul_f32_e64 v25, v25, v10
	v_pk_mul_f32 v[26:27], v[26:27], v[10:11] op_sel_hi:[1,0]
	v_pk_mul_f32 v[20:21], v[20:21], v[10:11] op_sel_hi:[1,0]
	v_pk_mul_f32 v[22:23], v[22:23], v[10:11] op_sel_hi:[1,0]
	v_bfe_u32 v19, v27, 16, 1
	v_bfe_u32 v40, v26, 16, 1
	v_bfe_u32 v41, v25, 16, 1
	v_bfe_u32 v42, v24, 16, 1
	v_add3_u32 v24, v24, v42, s33
	v_add3_u32 v25, v25, v41, s33
	v_add3_u32 v26, v26, v40, s33
	v_add3_u32 v19, v27, v19, s33
	v_bfe_u32 v27, v20, 16, 1
	v_bfe_u32 v40, v21, 16, 1
	v_bfe_u32 v41, v22, 16, 1
	v_bfe_u32 v42, v23, 16, 1
	v_add3_u32 v42, v23, v42, s33
	v_add3_u32 v41, v22, v41, s33
	v_add3_u32 v40, v21, v40, s33
	v_add3_u32 v27, v20, v27, s33
	v_lshrrev_b32_e32 v43, 16, v27
	v_lshrrev_b32_e32 v40, 16, v40
	v_lshrrev_b32_e32 v41, 16, v41
	v_lshrrev_b32_e32 v27, 16, v42
	v_and_or_b32 v27, v19, s29, v27
	v_and_or_b32 v26, v26, s29, v41
	v_and_or_b32 v25, v25, s29, v40
	v_and_or_b32 v24, v24, s29, v43
	s_waitcnt lgkmcnt(3)
	s_nop 1
	v_mfma_f32_16x16x32_bf16 v[20:23], v[204:207], v[24:27], v[28:31]
	s_waitcnt lgkmcnt(2)
	v_mfma_f32_16x16x32_bf16 v[28:31], v[208:211], v[24:27], v[36:39]
	s_waitcnt lgkmcnt(1)
	v_mfma_f32_16x16x32_bf16 v[36:39], v[212:215], v[24:27], v[44:47]
	s_waitcnt lgkmcnt(0)
	v_mfma_f32_16x16x32_bf16 v[24:27], v[216:219], v[24:27], v[32:35]
	ds_read2_b64 v[204:207], v11 offset0:56 offset1:60
	ds_read2_b64 v[208:211], v18 offset0:88 offset1:92
	ds_read2_b64 v[212:215], v68 offset0:120 offset1:124
	ds_read2_b64 v[216:219], v69 offset0:152 offset1:156
	v_mul_f32_e64 v16, v16, v10
	v_mul_f32_e64 v17, v17, v10
	v_pk_mul_f32 v[14:15], v[14:15], v[10:11] op_sel_hi:[1,0]
	v_pk_mul_f32 v[12:13], v[12:13], v[10:11] op_sel_hi:[1,0]
	v_pk_mul_f32 v[8:9], v[8:9], v[10:11] op_sel_hi:[1,0]
	v_bfe_u32 v10, v15, 16, 1
	v_bfe_u32 v32, v17, 16, 1
	v_bfe_u32 v33, v16, 16, 1
	v_add3_u32 v16, v16, v33, s33
	v_add3_u32 v17, v17, v32, s33
	v_add3_u32 v15, v15, v10, s33
	v_bfe_u32 v10, v12, 16, 1
	v_bfe_u32 v32, v8, 16, 1
	v_bfe_u32 v33, v9, 16, 1
	v_add3_u32 v33, v9, v33, s33
	v_add3_u32 v32, v8, v32, s33
	v_add3_u32 v12, v12, v10, s33
	v_bfe_u32 v19, v14, 16, 1
	v_add3_u32 v14, v14, v19, s33
	v_bfe_u32 v19, v13, 16, 1
	v_add3_u32 v13, v13, v19, s33
	v_lshrrev_b32_e32 v12, 16, v12
	v_lshrrev_b32_e32 v13, 16, v13
	v_lshrrev_b32_e32 v19, 16, v32
	v_lshrrev_b32_e32 v32, 16, v33
	v_and_or_b32 v35, v15, s29, v32
	v_and_or_b32 v34, v14, s29, v19
	v_and_or_b32 v33, v17, s29, v13
	v_and_or_b32 v32, v16, s29, v12
	s_waitcnt lgkmcnt(3)
	s_nop 1
	v_mfma_f32_16x16x32_bf16 v[20:23], v[204:207], v[32:35], v[20:23]
	s_waitcnt lgkmcnt(2)
	v_mfma_f32_16x16x32_bf16 v[16:19], v[208:211], v[32:35], v[28:31]
	s_waitcnt lgkmcnt(1)
	v_mfma_f32_16x16x32_bf16 v[12:15], v[212:215], v[32:35], v[36:39]
	s_waitcnt lgkmcnt(0)
	v_mfma_f32_16x16x32_bf16 v[8:11], v[216:219], v[32:35], v[24:27]
	s_and_saveexec_b64 s[2:3], s[0:1]
	s_cbranch_execz .LBB0_98
	s_nop 0
	v_bfe_u32 v26, v20, 16, 1
	v_add3_u32 v20, v20, v26, s33
	v_bfe_u32 v26, v21, 16, 1
	v_add3_u32 v21, v21, v26, s33
	v_lshrrev_b32_e32 v20, 16, v20
	v_add_u32_e32 v24, s6, v81
	v_and_or_b32 v20, v21, s29, v20
	v_bfe_u32 v21, v22, 16, 1
	v_ashrrev_i32_e32 v25, 31, v24
	v_add3_u32 v21, v22, v21, s33
	v_bfe_u32 v22, v23, 16, 1
	v_lshlrev_b64 v[24:25], 11, v[24:25]
	v_add3_u32 v22, v23, v22, s33
	v_lshrrev_b32_e32 v21, 16, v21
	v_lshl_add_u64 v[24:25], v[76:77], 0, v[24:25]
	v_and_or_b32 v21, v22, s29, v21
	global_store_dwordx2 v[24:25], v[20:21], off offset:1536
	v_bfe_u32 v20, v16, 16, 1
	v_add3_u32 v16, v16, v20, s33
	v_bfe_u32 v20, v17, 16, 1
	v_add3_u32 v17, v17, v20, s33
	v_lshrrev_b32_e32 v16, 16, v16
	v_and_or_b32 v16, v17, s29, v16
	v_bfe_u32 v17, v18, 16, 1
	v_add3_u32 v17, v18, v17, s33
	v_bfe_u32 v18, v19, 16, 1
	v_add3_u32 v18, v19, v18, s33
	v_lshrrev_b32_e32 v17, 16, v17
	v_and_or_b32 v17, v18, s29, v17
	global_store_dwordx2 v[24:25], v[16:17], off offset:1568
	v_bfe_u32 v16, v12, 16, 1
	v_add3_u32 v12, v12, v16, s33
	v_bfe_u32 v16, v13, 16, 1
	v_add3_u32 v13, v13, v16, s33
	v_lshrrev_b32_e32 v12, 16, v12
	v_and_or_b32 v12, v13, s29, v12
	v_bfe_u32 v13, v14, 16, 1
	v_add3_u32 v13, v14, v13, s33
	v_bfe_u32 v14, v15, 16, 1
	v_add3_u32 v14, v15, v14, s33
	v_lshrrev_b32_e32 v13, 16, v13
	v_and_or_b32 v13, v14, s29, v13
	global_store_dwordx2 v[24:25], v[12:13], off offset:1600
	v_bfe_u32 v12, v8, 16, 1
	v_add3_u32 v8, v8, v12, s33
	v_bfe_u32 v12, v9, 16, 1
	v_add3_u32 v9, v9, v12, s33
	v_lshrrev_b32_e32 v8, 16, v8
	v_and_or_b32 v8, v9, s29, v8
	v_bfe_u32 v9, v10, 16, 1
	v_add3_u32 v9, v10, v9, s33
	v_bfe_u32 v10, v11, 16, 1
	v_add3_u32 v10, v11, v10, s33
	v_lshrrev_b32_e32 v9, 16, v9
	v_and_or_b32 v9, v10, s29, v9
	global_store_dwordx2 v[24:25], v[8:9], off offset:1632
	s_branch .LBB0_98
